# P5 fully split: selection-only per token, column-sliced U phase (slice-major fp8 U table, partial dots), W pass (sum partials, gelu, gate), column-sliced V phase, H3 pass
# speedup vs baseline: 1.2269x; 1.0239x over previous
; __device__ __forceinline__ void convert_item_fp8(const float* __restrict__ src, unsigned char* __restrict__ dst, size_t item, float scale) {
;   size_t base = item * 8192 + (size_t)threadIdx.x * 16;
;   float4 a[2][4];
; #pragma unroll
;   for (int i = 0; i < 2; i++) {
;     const float4* q = (const float4*)(src + base + i * 4096);
; #pragma unroll
;     for (int j = 0; j < 4; j++) a[i][j] = q[j];
;   }
; #pragma unroll
;   for (int i = 0; i < 2; i++) {
;     unsigned o[4];
; #pragma unroll
;     for (int j = 0; j < 4; j++) {
;       int pk = __builtin_amdgcn_cvt_pk_fp8_f32(a[i][j].x * scale, a[i][j].y * scale, 0, false);
;       pk = __builtin_amdgcn_cvt_pk_fp8_f32(a[i][j].z * scale, a[i][j].w * scale, pk, true);
;       o[j] = (unsigned)pk;
;     }
;     *(uint4*)(dst + base + i * 4096) = make_uint4(o[0], o[1], o[2], o[3]);
;   }
; }
.LBB0_1179:
	s_add_u32 s8, s80, s8
	s_waitcnt lgkmcnt(0)
	v_accvgpr_read_b32 v0, a138
	s_addc_u32 s9, s81, s9
	s_lshl_b64 s[10:11], s[10:11], 13
	v_accvgpr_read_b32 v1, a139
	v_lshl_add_u64 v[40:41], s[10:11], 0, v[0:1]
	v_lshl_add_u64 v[24:25], v[40:41], 2, s[12:13]
	global_load_dwordx4 v[0:3], v[24:25], off
	global_load_dwordx4 v[4:7], v[24:25], off offset:16
	global_load_dwordx4 v[8:11], v[24:25], off offset:32
	global_load_dwordx4 v[12:15], v[24:25], off offset:48
	v_lshl_add_u64 v[28:29], v[24:25], 0, s[6:7]
	v_add_co_u32_e32 v24, vcc, s16, v24
	global_load_dwordx4 v[16:19], v[28:29], off offset:16
	global_load_dwordx4 v[20:23], v[28:29], off offset:32
	v_addc_co_u32_e32 v25, vcc, 0, v25, vcc
	global_load_dwordx4 v[24:27], v[24:25], off
	s_nop 0
	global_load_dwordx4 v[28:31], v[28:29], off offset:48
	v_mov_b32_e32 v32, 0
	v_mov_b32_e32 v34, 0
	v_mov_b32_e32 v37, 0
	v_mov_b32_e32 v33, 0
	v_mov_b32_e32 v35, 0
	v_mov_b32_e32 v36, 0
	v_mov_b32_e32 v38, 0
	v_mov_b32_e32 v39, 0
	v_and_b32_e32 v42, 0x380, v40
	v_lshrrev_b32_e32 v43, 3, v40
	v_lshlrev_b32_e32 v42, 14, v42
	v_and_b32_e32 v43, 0x1fff80, v43
	v_and_b32_e32 v40, 0x7f, v40
	v_or3_b32 v40, v40, v42, v43
	s_add_u32 s0, s0, s14
	v_lshl_add_u64 v[40:41], s[8:9], 0, v[40:41]
	v_add_co_u32_e32 v42, vcc, 0x200, v40
	s_addc_u32 s1, s1, s15
	s_nop 0
	v_addc_co_u32_e32 v43, vcc, 0, v41, vcc
	s_cmpk_lt_i32 s0, 0x1000
	s_waitcnt vmcnt(7)
	v_mul_f32_e32 v0, s17, v0
	v_mul_f32_e32 v1, s17, v1
	s_waitcnt vmcnt(5)
	v_mul_f32_e32 v8, s17, v8
	v_mul_f32_e32 v9, s17, v9
	v_cvt_pk_fp8_f32 v32, v0, v1
	v_mul_f32_e32 v4, s17, v4
	s_waitcnt vmcnt(3)
	v_mul_f32_e32 v0, s17, v16
	v_mul_f32_e32 v1, s17, v17
	v_mul_f32_e32 v5, s17, v5
	v_mul_f32_e32 v12, s17, v12
	v_mul_f32_e32 v13, s17, v13
	v_cvt_pk_fp8_f32 v34, v8, v9
	s_waitcnt vmcnt(2)
	v_mul_f32_e32 v8, s17, v20
	v_mul_f32_e32 v9, s17, v21
	s_waitcnt vmcnt(1)
	v_mul_f32_e32 v16, s17, v24
	v_mul_f32_e32 v17, s17, v25
	v_cvt_pk_fp8_f32 v37, v0, v1
	s_waitcnt vmcnt(0)
	v_mul_f32_e32 v0, s17, v28
	v_mul_f32_e32 v1, s17, v29
	v_cvt_pk_fp8_f32 v33, v4, v5
	v_cvt_pk_fp8_f32 v35, v12, v13
	v_cvt_pk_fp8_f32 v38, v8, v9
	v_cvt_pk_fp8_f32 v36, v16, v17
	v_cvt_pk_fp8_f32 v39, v0, v1
	v_mul_f32_e32 v2, s17, v2
	v_mul_f32_e32 v3, s17, v3
	v_mul_f32_e32 v6, s17, v6
	v_mul_f32_e32 v7, s17, v7
	v_mul_f32_e32 v10, s17, v10
	v_mul_f32_e32 v11, s17, v11
	v_mul_f32_e32 v14, s17, v14
	v_mul_f32_e32 v15, s17, v15
	v_mul_f32_e32 v4, s17, v18
	v_mul_f32_e32 v5, s17, v19
	v_mul_f32_e32 v12, s17, v22
	v_mul_f32_e32 v13, s17, v23
	v_mul_f32_e32 v18, s17, v26
	v_mul_f32_e32 v19, s17, v27
	v_mul_f32_e32 v8, s17, v30
	v_mul_f32_e32 v9, s17, v31
	v_cvt_pk_fp8_f32 v32, v2, v3 op_sel:[0,0,1]
	v_cvt_pk_fp8_f32 v33, v6, v7 op_sel:[0,0,1]
	v_cvt_pk_fp8_f32 v34, v10, v11 op_sel:[0,0,1]
	v_cvt_pk_fp8_f32 v35, v14, v15 op_sel:[0,0,1]
	v_cvt_pk_fp8_f32 v37, v4, v5 op_sel:[0,0,1]
	v_cvt_pk_fp8_f32 v38, v12, v13 op_sel:[0,0,1]
	v_cvt_pk_fp8_f32 v36, v18, v19 op_sel:[0,0,1]
	v_cvt_pk_fp8_f32 v39, v8, v9 op_sel:[0,0,1]
	global_store_dwordx4 v[40:41], v[32:35], off
	global_store_dwordx4 v[42:43], v[36:39], off
	s_cbranch_scc0 .LBB0_1182

; __device__ __forceinline__ void phase5(const Params& p, char* smem, const bool store_x = true) {
;     ...
;   for (int it = blockIdx.x; it < NT / 4; it += gridDim.x) {
;     const int tok = it * 4 + w;
;     float* xr = X + (size_t)tok * 1024 + lane * 16;
;     const float4 xv0 = *(const float4*)(xr), xv1 = *(const float4*)(xr + 4), xv2 = *(const float4*)(xr + 8), xv3 = *(const float4*)(xr + 12);
;     ((uint4*)tsL)[lane] = pf_ts;
;     ((uint4*)tiL)[lane] = pf_ti;
;     const uint4 cur_ha = pf_ha, cur_hb = pf_hb; const float cur_rs = rsqrtf(pf_ss * (1.f / 1024.f) + EPSF);
;     {
;       const int itn = it + (int)gridDim.x;
;       if (itn < NT / 4) {
;         const int tokn = itn * 4 + w;
;         pf_ts = ((const uint4*)(TOPS + (size_t)tokn * 256))[lane];
;         pf_ti = ((const uint4*)(TOPI + (size_t)tokn * 256))[lane];
;         pf_ha = *(const uint4*)(X1B + (size_t)tokn * 1024 + lane * 16);
;         pf_hb = *(const uint4*)(X1B + (size_t)tokn * 1024 + lane * 16 + 8);
;         pf_ss = SSQ1[tokn];
;       }
;     }
;     {
;       const int hd = lane >> 3, g = lane & 7;
;       const float* ts = tsL + hd * 32;
;       const int* ti = tiL + hd * 32;
;       float key[7]; int ij[7];
; #pragma unroll
;       for (int sl = 0; sl < 7; sl++) {
;         const int cid = g * 7 + sl;
;         const int t = ctab[cid];
;         ij[sl] = t;
;         float sum = ts[t >> 4] + ts[16 + (t & 15)];
;         unsigned k = (__float_as_uint(sum) & ~63u) | (unsigned)cid;
;         key[sl] = cid < 50 ? __uint_as_float(k) : NINF;
;       }
.LBB0_1482:
	v_accvgpr_read_b32 v0, a129
	v_lshl_add_u32 v32, s44, 2, v0
	v_ashrrev_i32_e32 v33, 31, v32
	v_accvgpr_read_b32 v2, a70
	v_lshlrev_b64 v[0:1], 12, v[32:33]
	v_accvgpr_read_b32 v3, a71
	v_lshl_add_u64 v[198:199], v[2:3], 0, v[0:1]
	s_add_i32 s44, s44, s82
	s_cmpk_gt_i32 s44, 0x107f
	s_cselect_b64 s[34:35], -1, 0
	v_accvgpr_write_b32 a12, v96
	v_accvgpr_write_b32 a14, v98
	v_accvgpr_write_b32 a8, v100
	v_accvgpr_write_b32 a10, v102
	s_and_b64 vcc, exec, s[34:35]
	v_accvgpr_write_b32 a13, v97
	v_accvgpr_write_b32 a15, v99
	v_accvgpr_write_b32 a9, v101
	v_accvgpr_write_b32 a11, v103
	ds_write_b128 v177, a[0:3] offset:2048
	ds_write_b128 v177, a[4:7] offset:3072
	s_cbranch_vccnz .LBB0_1484
	v_accvgpr_read_b32 v0, a129
	v_lshl_add_u32 v0, s44, 2, v0
	v_ashrrev_i32_e32 v1, 31, v0
	v_accvgpr_read_b32 v4, a72
	v_accvgpr_read_b32 v6, a74
	v_lshlrev_b64 v[2:3], 10, v[0:1]
	v_accvgpr_read_b32 v5, a73
	v_accvgpr_read_b32 v7, a75
	v_lshl_add_u64 v[4:5], v[4:5], 0, v[2:3]
	v_lshl_add_u64 v[2:3], v[6:7], 0, v[2:3]
	global_load_dwordx4 a[0:3], v[4:5], off
	global_load_dwordx4 a[4:7], v[2:3], off
	v_lshlrev_b64 v[2:3], 11, v[0:1]
	v_lshl_add_u64 v[2:3], v[188:189], 0, v[2:3]
	v_lshl_add_u64 v[0:1], v[0:1], 2, s[94:95]
.LBB0_1484:
	ds_read_u8 v0, v238 offset:16384
	ds_read_u8 v1, v238 offset:16385
	ds_read_u8 v2, v238 offset:16386
	ds_read_u8 v3, v238 offset:16387
	ds_read_u8 v4, v238 offset:16388
	ds_read_u8 v5, v238 offset:16389
	ds_read_u8 v6, v238 offset:16390
	s_waitcnt lgkmcnt(6)
	v_lshrrev_b32_e32 v7, 2, v0
	v_and_b32_e32 v0, 15, v0
	v_lshl_add_u32 v47, v0, 2, v179
	s_waitcnt lgkmcnt(5)
	v_lshrrev_b32_e32 v0, 2, v1
	v_and_b32_e32 v0, 60, v0
	v_add_u32_e32 v44, v179, v0
	v_and_b32_e32 v0, 15, v1
	v_lshl_add_u32 v45, v0, 2, v179
	s_waitcnt lgkmcnt(4)
	v_lshrrev_b32_e32 v0, 2, v2
	v_and_b32_e32 v0, 60, v0
	v_add_u32_e32 v42, v179, v0
	v_and_b32_e32 v0, 15, v2
	v_lshl_add_u32 v43, v0, 2, v179
	s_waitcnt lgkmcnt(3)
	v_lshrrev_b32_e32 v0, 2, v3
	v_and_b32_e32 v0, 60, v0
	v_add_u32_e32 v40, v179, v0
	v_and_b32_e32 v0, 15, v3
	v_lshl_add_u32 v41, v0, 2, v179
	s_waitcnt lgkmcnt(2)
	v_lshrrev_b32_e32 v0, 2, v4
	v_and_b32_e32 v0, 60, v0
	v_add_u32_e32 v38, v179, v0
	v_and_b32_e32 v0, 15, v4
	v_lshl_add_u32 v39, v0, 2, v179
	s_waitcnt lgkmcnt(1)
	v_lshrrev_b32_e32 v0, 2, v5
	v_and_b32_e32 v0, 60, v0
	v_and_b32_e32 v7, 60, v7
	v_add_u32_e32 v36, v179, v0
	v_and_b32_e32 v0, 15, v5
	v_add_u32_e32 v46, v179, v7
	v_lshl_add_u32 v37, v0, 2, v179
	s_waitcnt lgkmcnt(0)
	v_lshrrev_b32_e32 v0, 2, v6
	ds_read_b32 v48, v46 offset:2048
	ds_read_b32 v52, v47 offset:2112
	ds_read_b32 v51, v44 offset:2048
	ds_read_b32 v55, v45 offset:2112
	ds_read_b32 v50, v42 offset:2048
	ds_read_b32 v54, v43 offset:2112
	ds_read_b32 v49, v40 offset:2048
	ds_read_b32 v53, v41 offset:2112
	v_and_b32_e32 v0, 60, v0
	v_add_u32_e32 v34, v179, v0
	v_and_b32_e32 v0, 15, v6
	v_lshl_add_u32 v35, v0, 2, v179
	ds_read_b32 v59, v38 offset:2048
	ds_read_b32 v61, v39 offset:2112
	ds_read_b32 v57, v36 offset:2048
	ds_read_b32 v60, v37 offset:2112
	ds_read_b32 v56, v34 offset:2048
	ds_read_b32 v58, v35 offset:2112
	s_and_saveexec_b64 s[0:1], s[4:5]
	v_accvgpr_read_b32 v0, a76
	ds_write_b32 v0, a69 offset:1536
	s_or_b64 exec, exec, s[0:1]
	s_waitcnt lgkmcnt(12)
	v_add_f32_e32 v0, v48, v52
	v_and_or_b32 v52, v0, s33, v238
	s_waitcnt lgkmcnt(10)
	v_add_f32_e32 v0, v51, v55
	v_accvgpr_read_b32 v1, a68
	v_and_or_b32 v0, v0, s33, v1
	v_cndmask_b32_e64 v48, v0, v252, s[16:17]
	s_waitcnt lgkmcnt(8)
	v_add_f32_e32 v0, v50, v54
	v_and_or_b32 v0, v0, s33, v251
	v_cndmask_b32_e64 v51, v0, v252, s[16:17]
	s_waitcnt lgkmcnt(6)
	v_add_f32_e32 v0, v49, v53
	v_and_or_b32 v0, v0, s33, v181
	v_lshlrev_b64 v[200:201], 10, v[32:33]
	v_cndmask_b32_e64 v32, v0, v252, s[16:17]
	s_waitcnt lgkmcnt(4)
	v_add_f32_e32 v0, v59, v61
	v_and_or_b32 v0, v0, s33, v184
	v_cndmask_b32_e64 v33, v0, v252, s[16:17]
	s_waitcnt lgkmcnt(2)
	v_add_f32_e32 v0, v57, v60
	v_and_or_b32 v0, v0, s33, v245
	v_cndmask_b32_e64 v49, v0, v252, s[16:17]
	s_waitcnt lgkmcnt(0)
	v_add_f32_e32 v0, v56, v58
	v_and_or_b32 v0, v0, s33, v250
	v_cndmask_b32_e64 v50, v0, v252, s[16:17]
	v_max_f32_e32 v0, v52, v52
	v_max_f32_e32 v53, 0xff61b1e6, v0
	v_mov_b32_e32 v55, 0
	v_mov_b32_e32 v54, 0x7f61b1e6
	s_mov_b32 s0, 16

; #define DPP_F(v, ctrl) __int_as_float(__builtin_amdgcn_update_dpp(0, __float_as_int(v), (ctrl), 0xF, 0xF, true))
; __device__ __forceinline__ void phase5(const Params& p, char* smem, const bool store_x = true) {
;     ...
;       float ev[7]; float es = 0.f;
; #pragma unroll
;       for (int sl = 0; sl < 7; sl++) { ev[sl] = key[sl] >= m ? __expf(key[sl] - m1) : 0.f; es += ev[sl]; }
;       es += DPP_F(es, 0xB1); es += DPP_F(es, 0x4E); es += DPP_F(es, 0x141);
;       const float inv = 1.f / es;
; #pragma unroll
;       for (int sl = 0; sl < 7; sl++) {
;         if (key[sl] >= m) {
;           int pos = atomicAdd(&wcnt[hd], 1);
;           int ia = ti[ij[sl] >> 4], ib = ti[16 + (ij[sl] & 15)];
;           widx[hd * 16 + pos] = ia * 128 + ib;
;           wgate[hd * 16 + pos] = ev[sl] * inv;
;         }
;       }
.LBB0_1496:
	s_or_b64 exec, exec, s[18:19]
	v_mbcnt_lo_u32_b32 v0, -1, 0
	v_mbcnt_hi_u32_b32 v0, -1, v0
	v_lshl_add_u32 v1, v0, 3, v176
	ds_read_b64 v[2:3], v1
	ds_read_b64 v[4:5], v1 offset:512
	s_add_u32 s98, s80, 0x3bb5000
	s_addc_u32 s99, s81, 0
	v_lshl_add_u32 v6, v0, 3, v200
	v_lshrrev_b32_e32 v7, 8, v200
	v_add_u32_e32 v7, 0x1100000, v7
	v_mov_b32_e32 v20, 0
	s_waitcnt lgkmcnt(0)
	v_lshlrev_b32_e32 v16, 7, v2
	v_lshlrev_b32_e32 v17, 7, v3
	global_store_dwordx2 v6, v[16:17], s[98:99]
	global_store_dwordx2 v6, v[4:5], s[98:99] offset:512
	s_mov_b64 exec, 1
	global_store_dword v7, v20, s[98:99]
	s_mov_b64 exec, -1
	s_waitcnt vmcnt(0)
	s_and_b64 vcc, exec, s[34:35]
	s_cbranch_vccnz .Lp5a_done
	s_branch .LBB0_1482

; __device__ __forceinline__ void phase5(const Params& p, char* smem, const bool store_x = true) {
;     ...
; #pragma unroll
;       for (int sl = 0; sl < 7; sl++) {
;         if (key[sl] >= m) {
;           int pos = atomicAdd(&wcnt[hd], 1);
;           int ia = ti[ij[sl] >> 4], ib = ti[16 + (ij[sl] & 15)];
;           widx[hd * 16 + pos] = ia * 128 + ib;
;           wgate[hd * 16 + pos] = ev[sl] * inv;
;         }
;       }
; __device__ __forceinline__ void xcd_barrier(const XcdBarrier& b) {
;     asm volatile("s_waitcnt vmcnt(0)" ::: "memory");
;     __syncthreads();
;     if (threadIdx.x == 0) {
;         unsigned* bar = b.bar;
.LBB0_1521:
	ds_add_rtn_u32 v0, v253, v178 offset:1536
	ds_read_b32 v1, v36 offset:3072
	ds_read_b32 v2, v37 offset:3136
	s_waitcnt lgkmcnt(2)
	v_add_u32_e32 v0, v0, v239
	s_waitcnt lgkmcnt(0)
	v_lshl_add_u32 v1, v1, 7, v2
	v_lshl_add_u32 v0, v0, 2, v176
	v_mul_f32_e32 v2, v33, v49
	ds_write2st64_b32 v0, v1, v2 offset1:2
	s_or_b64 exec, exec, s[20:21]
	s_and_saveexec_b64 s[18:19], s[0:1]
	s_cbranch_execnz .LBB0_1495
	s_branch .LBB0_1496
.Lp5a_done:
.Lpb1_1523:
	s_waitcnt vmcnt(0)
	s_barrier
	s_and_saveexec_b64 s[0:1], s[72:73]
	s_cbranch_execz .Lpb1_1575

; __device__ __forceinline__ void xcd_barrier(const XcdBarrier& b) {
;     ...
;         __builtin_amdgcn_s_waitcnt(0);
;         unsigned nloc = b.st[0], nx = b.st[1];
;         if (nloc == 0u) { xcd_barrier_complete(bar, b.x, nloc, nx); b.st[0] = nloc; b.st[1] = nx; }
	v_mov_b32_e32 v0, 0x23800
	s_waitcnt vmcnt(0) expcnt(0) lgkmcnt(0)
	ds_read_b32 v2, v0
	v_mov_b32_e32 v0, 0x23804
	ds_read_b32 v0, v0
	s_waitcnt lgkmcnt(1)
	v_cmp_ne_u32_e32 vcc, 0, v2
	s_cbranch_vccnz .Lpb1_1539

; __device__ __forceinline__ unsigned xb_ld(unsigned* p)              { return __hip_atomic_load(p, __ATOMIC_RELAXED, __HIP_MEMORY_SCOPE_AGENT); }
; __device__ __forceinline__ void xcd_barrier_complete(unsigned* bar, unsigned x, unsigned& nloc, unsigned& nx) {
;     const unsigned G = gridDim.x * gridDim.y * gridDim.z;
;     unsigned sum, cnt, mine, sp = 0u;
;     for (;;) {
;         sum = 0u; cnt = 0u; mine = 0u;
; #pragma unroll
;         for (unsigned j = 0; j < 16; ++j) { const unsigned c = xb_ld(&bar[XB_XCNT(j)]); sum += c; cnt += (c > 0u) ? 1u : 0u; mine = (j == x) ? c : mine; }
;         if (sum == G) break;
;         __builtin_amdgcn_s_sleep(1);
;         if ((++sp & 255u) == 0u) { if (xb_ld(&bar[XB_TMO])) break; if (sp > XB_SPIN_CAP) { atomicAdd(&bar[XB_TMO], 1u); break; } }
	v_readlane_b32 s4, v254, 0
	s_mul_i32 s33, s83, s4
	s_add_u32 s4, s80, 0x12f35200
	s_addc_u32 s5, s81, 0
	s_add_u32 s6, s80, 0x12f35400
	s_addc_u32 s7, s81, 0
	s_add_u32 s8, s80, 0x12f35500
	s_addc_u32 s9, s81, 0
	s_add_u32 s10, s80, 0x12f35600
	s_addc_u32 s11, s81, 0
	s_add_u32 s12, s80, 0x12f35700
	s_addc_u32 s13, s81, 0
	s_add_u32 s14, s80, 0x12f35800
	s_addc_u32 s15, s81, 0
	s_add_u32 s16, s80, 0x12f35900
	s_addc_u32 s17, s81, 0
	s_add_u32 s18, s80, 0x12f35a00
	s_addc_u32 s19, s81, 0
	s_add_u32 s20, s80, 0x12f35b00
	s_addc_u32 s21, s81, 0
	s_add_u32 s22, s80, 0x12f35c00
	s_addc_u32 s23, s81, 0
	s_add_u32 s24, s80, 0x12f35d00
	s_addc_u32 s25, s81, 0
	s_add_u32 s26, s80, 0x12f35e00
	s_addc_u32 s27, s81, 0
	s_add_u32 s28, s80, 0x12f35f00
	s_addc_u32 s29, s81, 0
	s_add_u32 s34, s80, 0x12f36000
	s_addc_u32 s35, s81, 0
	s_add_u32 s36, s80, 0x12f36100
	s_addc_u32 s37, s81, 0
	s_add_u32 s38, s80, 0x12f36200
	s_addc_u32 s39, s81, 0
	s_add_u32 s40, s80, 0x12f36300
	s_mul_i32 s33, s33, s82
	s_addc_u32 s41, s81, 0
	s_mov_b32 s48, 1
	v_mov_b32_e32 v16, 0
	s_branch .Lpb1_1527

; __device__ __forceinline__ float bflo(unsigned u) { return __uint_as_float(u << 16); }
; __device__ __forceinline__ float bfhi(unsigned u) { return __uint_as_float(u & 0xffff0000u); }
; #define P5_LOAD(A, TAB, j0)                                                                \
;   _Pragma("unroll") for (int q = 0; q < 16; q++) {                                         \
;     A[q] = ((const uint4*)((TAB) + (size_t)widx[(j0) + q] * 1024))[lane];                  \
;   }
; __device__ __forceinline__ void phase5(const Params& p, char* smem, const bool store_x = true) {
;     ...
;     float2v h2[8];
;     {
;       const uint4 a = cur_ha;
;       const uint4 b2 = cur_hb;
;       h2[0] = float2v{bflo(a.x), bfhi(a.x)}; h2[1] = float2v{bflo(a.y), bfhi(a.y)}; h2[2] = float2v{bflo(a.z), bfhi(a.z)}; h2[3] = float2v{bflo(a.w), bfhi(a.w)};
;       h2[4] = float2v{bflo(b2.x), bfhi(b2.x)}; h2[5] = float2v{bflo(b2.y), bfhi(b2.y)}; h2[6] = float2v{bflo(b2.z), bfhi(b2.z)}; h2[7] = float2v{bflo(b2.w), bfhi(b2.w)};
; #pragma unroll
;       for (int i = 0; i < 8; i++) h2[i] = h2[i] * gf[i] * cur_rs;
;     }
;     uint4 A0[16], A1[16];
;     P5_LOAD(A0, EU, 0)
; #pragma unroll 1
;     for (int j0 = 0; j0 < 128; j0 += 32) {
;       P5_LOAD(A1, EU, j0 + 16)
;       P5_COMPUTE_U(A0, j0)
;       if (j0 + 32 < 128) { P5_LOAD(A0, EU, j0 + 32) } else { P5_LOAD(A0, EV, 0) }
;       P5_COMPUTE_U(A1, j0 + 16)
;     }
.Lp5u_start:
	v_mbcnt_lo_u32_b32 v0, -1, 0
	v_mbcnt_hi_u32_b32 v0, -1, v0
	v_accvgpr_read_b32 v4, a129
	v_readlane_b32 s28, v254, 23
	v_readlane_b32 s29, v254, 24
	s_and_b32 s0, s96, 7
	s_lshr_b32 s1, s96, 3
	v_and_b32_e32 v1, 7, v0
	v_lshrrev_b32_e32 v2, 3, v0
	v_lshlrev_b32_e32 v3, 3, v0
	v_lshlrev_b32_e32 v7, 5, v1
	v_lshlrev_b32_e32 v9, 6, v1
	v_lshlrev_b32_e32 v1, 4, v1
	v_lshlrev_b32_e32 v2, 6, v2
	v_readfirstlane_b32 s8, v4
	s_lshl_b32 s17, s8, 13
	v_add_u32_e32 v2, s17, v2
	s_lshl_b32 s10, s1, 2
	s_add_u32 s8, s8, s10
	s_lshr_b32 s9, s82, 1
	s_lshl_b32 s10, s0, 21
	s_add_u32 s2, s80, 0xaf35000
	s_addc_u32 s3, s81, 0
	s_add_u32 s2, s2, s10
	s_addc_u32 s3, s3, 0
	s_add_u32 s4, s80, 0x3bb5000
	s_addc_u32 s5, s81, 0
	s_lshl_b32 s10, s0, 9
	s_add_u32 s6, s80, 0xcf35000
	s_addc_u32 s7, s81, 0
	s_add_u32 s6, s6, s10
	s_addc_u32 s7, s7, 0
	s_lshl_b32 s10, s0, 8
	s_add_u32 s36, s80, 0x8e35000
	s_addc_u32 s37, s81, 0
	s_add_u32 s36, s36, s10
	s_addc_u32 s37, s37, 0
	s_add_u32 s38, s80, 0x3b94000
	s_addc_u32 s39, s81, 0
	s_lshl_b32 s10, s0, 9
	s_add_u32 s28, s28, s10
	s_addc_u32 s29, s29, 0
	global_load_dwordx4 a[48:51], v9, s[28:29]
	global_load_dwordx4 a[52:55], v9, s[28:29] offset:16
	global_load_dwordx4 a[56:59], v9, s[28:29] offset:32
	global_load_dwordx4 a[60:63], v9, s[28:29] offset:48
	s_movk_i32 s13, 0x41ff
	s_mov_b32 s14, 0xf0f0f0f0
	s_mov_b32 s15, 0xf0f0f0f0
	s_mov_b32 s40, 0xcccccccc
	s_mov_b32 s41, 0xcccccccc
	s_mov_b32 s42, 0xaaaaaaaa
	s_mov_b32 s43, 0xaaaaaaaa
	s_mov_b32 s33, 0x800000
	v_mov_b32_e32 v57, 0x358637bd
	s_mov_b32 s16, 0
	s_mov_b32 s19, 0
	v_lshlrev_b32_e32 v9, 4, v0
	v_mov_b32_e32 v59, s5
	v_add_co_u32_e32 v58, vcc, s4, v9
	s_nop 1
	v_addc_co_u32_e32 v59, vcc, 0, v59, vcc
	s_mul_i32 s20, s9, 1
	s_mul_i32 s21, s9, 2
	s_mul_i32 s22, s9, 3
	s_mul_i32 s23, s9, 4
	s_mul_i32 s24, s9, 5
	s_mul_i32 s25, s9, 6
	s_mul_i32 s26, s9, 7
	s_mul_i32 s27, s9, 8
	s_min_u32 s10, s8, s13
	s_lshl_b32 s18, s10, 10
	s_add_u32 s11, s16, 0
	s_and_b32 s11, s11, 7
	s_lshl_b32 s11, s11, 10
	s_add_u32 s11, s11, s17
	s_mov_b32 m0, s11
	v_lshl_add_u64 v[4:5], v[58:59], 0, s[18:19]
	global_load_lds_dwordx4 v[4:5], off
	s_add_u32 s10, s8, s20
	s_min_u32 s10, s10, s13
	s_lshl_b32 s18, s10, 10
	s_add_u32 s11, s16, 1
	s_and_b32 s11, s11, 7
	s_lshl_b32 s11, s11, 10
	s_add_u32 s11, s11, s17
	s_mov_b32 m0, s11
	v_lshl_add_u64 v[4:5], v[58:59], 0, s[18:19]
	global_load_lds_dwordx4 v[4:5], off
	s_add_u32 s10, s8, s21
	s_min_u32 s10, s10, s13
	s_lshl_b32 s18, s10, 10
	s_add_u32 s11, s16, 2
	s_and_b32 s11, s11, 7
	s_lshl_b32 s11, s11, 10
	s_add_u32 s11, s11, s17
	s_mov_b32 m0, s11
	v_lshl_add_u64 v[4:5], v[58:59], 0, s[18:19]
	global_load_lds_dwordx4 v[4:5], off
	s_add_u32 s10, s8, s22
	s_min_u32 s10, s10, s13
	s_lshl_b32 s18, s10, 10
	s_add_u32 s11, s16, 3
	s_and_b32 s11, s11, 7
	s_lshl_b32 s11, s11, 10
	s_add_u32 s11, s11, s17
	s_mov_b32 m0, s11
	v_lshl_add_u64 v[4:5], v[58:59], 0, s[18:19]
	global_load_lds_dwordx4 v[4:5], off
	s_add_u32 s10, s8, s23
	s_min_u32 s10, s10, s13
	s_lshl_b32 s18, s10, 10
	s_add_u32 s11, s16, 4
	s_and_b32 s11, s11, 7
	s_lshl_b32 s11, s11, 10
	s_add_u32 s11, s11, s17
	s_mov_b32 m0, s11
	v_lshl_add_u64 v[4:5], v[58:59], 0, s[18:19]
	global_load_lds_dwordx4 v[4:5], off
	s_add_u32 s10, s8, s24
	s_min_u32 s10, s10, s13
	s_lshl_b32 s18, s10, 10
	s_add_u32 s11, s16, 5
	s_and_b32 s11, s11, 7
	s_lshl_b32 s11, s11, 10
	s_add_u32 s11, s11, s17
	s_mov_b32 m0, s11
	v_lshl_add_u64 v[4:5], v[58:59], 0, s[18:19]
	global_load_lds_dwordx4 v[4:5], off
	s_waitcnt vmcnt(0)
	s_add_u32 s11, s16, 0
	s_and_b32 s11, s11, 7
	s_lshl_b32 s11, s11, 10
	v_add_u32_e32 v8, s11, v2
	ds_read_b128 v[10:13], v8 offset:0
	ds_read_b128 v[14:17], v8 offset:16
	ds_read_b128 v[18:21], v8 offset:32
	ds_read_b128 v[22:25], v8 offset:48
	s_min_u32 s10, s8, s13
	s_lshl_b32 s11, s10, 11
	v_add_u32_e32 v6, s11, v7
	global_load_dwordx4 a[0:3], v6, s[36:37]
	global_load_dwordx4 a[4:7], v6, s[36:37] offset:16
	s_lshl_b32 s11, s10, 2
	v_mov_b32_e32 v6, s11
	global_load_dword a8, v6, s[38:39]
	s_waitcnt lgkmcnt(0)
	v_add_u32_e32 v10, v10, v1
	global_load_dwordx4 v[60:63], v10, s[2:3]
	v_add_u32_e32 v11, v11, v1
	global_load_dwordx4 v[64:67], v11, s[2:3]
	v_add_u32_e32 v12, v12, v1
	global_load_dwordx4 v[68:71], v12, s[2:3]
	v_add_u32_e32 v13, v13, v1
	global_load_dwordx4 v[72:75], v13, s[2:3]
	v_add_u32_e32 v14, v14, v1
	global_load_dwordx4 v[76:79], v14, s[2:3]
	v_add_u32_e32 v15, v15, v1
	global_load_dwordx4 v[80:83], v15, s[2:3]
	v_add_u32_e32 v16, v16, v1
	global_load_dwordx4 v[84:87], v16, s[2:3]
	v_add_u32_e32 v17, v17, v1
	global_load_dwordx4 v[88:91], v17, s[2:3]
	v_add_u32_e32 v18, v18, v1
	global_load_dwordx4 v[92:95], v18, s[2:3]
	v_add_u32_e32 v19, v19, v1
	global_load_dwordx4 v[96:99], v19, s[2:3]
	v_add_u32_e32 v20, v20, v1
	global_load_dwordx4 v[100:103], v20, s[2:3]
	v_add_u32_e32 v21, v21, v1
	global_load_dwordx4 v[104:107], v21, s[2:3]
	v_add_u32_e32 v22, v22, v1
	global_load_dwordx4 v[108:111], v22, s[2:3]
	v_add_u32_e32 v23, v23, v1
	global_load_dwordx4 v[112:115], v23, s[2:3]
	v_add_u32_e32 v24, v24, v1
	global_load_dwordx4 v[116:119], v24, s[2:3]
	v_add_u32_e32 v25, v25, v1
	global_load_dwordx4 v[120:123], v25, s[2:3]
	global_load_dword v252, v6, s[38:39]
	global_load_dword v252, v6, s[38:39]
	s_add_u32 s11, s16, 1
	s_and_b32 s11, s11, 7
	s_lshl_b32 s11, s11, 10
	v_add_u32_e32 v8, s11, v2
	ds_read_b128 v[10:13], v8 offset:0
	ds_read_b128 v[14:17], v8 offset:16
	ds_read_b128 v[18:21], v8 offset:32
	ds_read_b128 v[22:25], v8 offset:48
	s_add_u32 s10, s8, s20
	s_min_u32 s10, s10, s13
	s_lshl_b32 s11, s10, 11
	v_add_u32_e32 v6, s11, v7
	global_load_dwordx4 a[16:19], v6, s[36:37]
	global_load_dwordx4 a[20:23], v6, s[36:37] offset:16
	s_lshl_b32 s11, s10, 2
	v_mov_b32_e32 v6, s11
	global_load_dword a24, v6, s[38:39]
	s_waitcnt lgkmcnt(0)
	v_add_u32_e32 v10, v10, v1
	global_load_dwordx4 v[124:127], v10, s[2:3]
	v_add_u32_e32 v11, v11, v1
	global_load_dwordx4 v[128:131], v11, s[2:3]
	v_add_u32_e32 v12, v12, v1
	global_load_dwordx4 v[132:135], v12, s[2:3]
	v_add_u32_e32 v13, v13, v1
	global_load_dwordx4 v[136:139], v13, s[2:3]
	v_add_u32_e32 v14, v14, v1
	global_load_dwordx4 v[140:143], v14, s[2:3]
	v_add_u32_e32 v15, v15, v1
	global_load_dwordx4 v[144:147], v15, s[2:3]
	v_add_u32_e32 v16, v16, v1
	global_load_dwordx4 v[148:151], v16, s[2:3]
	v_add_u32_e32 v17, v17, v1
	global_load_dwordx4 v[152:155], v17, s[2:3]
	v_add_u32_e32 v18, v18, v1
	global_load_dwordx4 v[156:159], v18, s[2:3]
	v_add_u32_e32 v19, v19, v1
	global_load_dwordx4 v[160:163], v19, s[2:3]
	v_add_u32_e32 v20, v20, v1
	global_load_dwordx4 v[164:167], v20, s[2:3]
	v_add_u32_e32 v21, v21, v1
	global_load_dwordx4 v[168:171], v21, s[2:3]
	v_add_u32_e32 v22, v22, v1
	global_load_dwordx4 v[172:175], v22, s[2:3]
	v_add_u32_e32 v23, v23, v1
	global_load_dwordx4 v[176:179], v23, s[2:3]
	v_add_u32_e32 v24, v24, v1
	global_load_dwordx4 v[180:183], v24, s[2:3]
	v_add_u32_e32 v25, v25, v1
	global_load_dwordx4 v[184:187], v25, s[2:3]
	global_load_dword v252, v6, s[38:39]
; __device__ __forceinline__ float bflo(unsigned u) { return __uint_as_float(u << 16); }
; __device__ __forceinline__ float bfhi(unsigned u) { return __uint_as_float(u & 0xffff0000u); }
; __device__ __forceinline__ void phase5(const Params& p, char* smem, const bool store_x = true) {
;     ...
;     float2v h2[8];
;     {
;       const uint4 a = cur_ha;
;       const uint4 b2 = cur_hb;
;       h2[0] = float2v{bflo(a.x), bfhi(a.x)}; h2[1] = float2v{bflo(a.y), bfhi(a.y)}; h2[2] = float2v{bflo(a.z), bfhi(a.z)}; h2[3] = float2v{bflo(a.w), bfhi(a.w)};
;       h2[4] = float2v{bflo(b2.x), bfhi(b2.x)}; h2[5] = float2v{bflo(b2.y), bfhi(b2.y)}; h2[6] = float2v{bflo(b2.z), bfhi(b2.z)}; h2[7] = float2v{bflo(b2.w), bfhi(b2.w)};
; #pragma unroll
;       for (int i = 0; i < 8; i++) h2[i] = h2[i] * gf[i] * cur_rs;
;     }
.Lp5u_loop:
	s_add_u32 s10, s8, s25
	s_min_u32 s10, s10, s13
	s_lshl_b32 s18, s10, 10
	s_add_u32 s11, s16, 6
	s_and_b32 s11, s11, 7
	s_lshl_b32 s11, s11, 10
	s_add_u32 s11, s11, s17
	s_mov_b32 m0, s11
	v_lshl_add_u64 v[4:5], v[58:59], 0, s[18:19]
	global_load_lds_dwordx4 v[4:5], off
	s_add_u32 s11, s16, 2
	s_and_b32 s11, s11, 7
	s_lshl_b32 s11, s11, 10
	v_add_u32_e32 v8, s11, v2
	ds_read_b128 v[10:13], v8 offset:0
	ds_read_b128 v[14:17], v8 offset:16
	ds_read_b128 v[18:21], v8 offset:32
	ds_read_b128 v[22:25], v8 offset:48
	s_add_u32 s10, s8, s21
	s_min_u32 s10, s10, s13
	s_lshl_b32 s11, s10, 11
	v_add_u32_e32 v6, s11, v7
	global_load_dwordx4 a[32:35], v6, s[36:37]
	global_load_dwordx4 a[36:39], v6, s[36:37] offset:16
	s_lshl_b32 s11, s10, 2
	v_mov_b32_e32 v6, s11
	global_load_dword a40, v6, s[38:39]
	s_waitcnt lgkmcnt(0)
	v_add_u32_e32 v10, v10, v1
	global_load_dwordx4 v[188:191], v10, s[2:3]
	v_add_u32_e32 v11, v11, v1
	global_load_dwordx4 v[192:195], v11, s[2:3]
	v_add_u32_e32 v12, v12, v1
	global_load_dwordx4 v[196:199], v12, s[2:3]
	v_add_u32_e32 v13, v13, v1
	global_load_dwordx4 v[200:203], v13, s[2:3]
	v_add_u32_e32 v14, v14, v1
	global_load_dwordx4 v[204:207], v14, s[2:3]
	v_add_u32_e32 v15, v15, v1
	global_load_dwordx4 v[208:211], v15, s[2:3]
	v_add_u32_e32 v16, v16, v1
	global_load_dwordx4 v[212:215], v16, s[2:3]
	v_add_u32_e32 v17, v17, v1
	global_load_dwordx4 v[216:219], v17, s[2:3]
	v_add_u32_e32 v18, v18, v1
	global_load_dwordx4 v[220:223], v18, s[2:3]
	v_add_u32_e32 v19, v19, v1
	global_load_dwordx4 v[224:227], v19, s[2:3]
	v_add_u32_e32 v20, v20, v1
	global_load_dwordx4 v[228:231], v20, s[2:3]
	v_add_u32_e32 v21, v21, v1
	global_load_dwordx4 v[232:235], v21, s[2:3]
	v_add_u32_e32 v22, v22, v1
	global_load_dwordx4 v[236:239], v22, s[2:3]
	v_add_u32_e32 v23, v23, v1
	global_load_dwordx4 v[240:243], v23, s[2:3]
	v_add_u32_e32 v24, v24, v1
	global_load_dwordx4 v[244:247], v24, s[2:3]
	v_add_u32_e32 v25, v25, v1
	global_load_dwordx4 v[248:251], v25, s[2:3]
	s_mov_b32 s12, s8
	s_waitcnt vmcnt(42)
	s_cmp_lt_u32 s12, 0x4200
	s_cbranch_scc0 .Lp5u_skip0
	v_accvgpr_read_b32 v56, a8
	v_fmamk_f32 v56, v56, 0x3a800000, v57
	v_mul_f32_e32 v9, 0x4b800000, v56
	v_cmp_gt_f32_e32 vcc, s33, v56
	s_nop 1
	v_cndmask_b32_e32 v56, v56, v9, vcc
	v_rsq_f32_e32 v56, v56
	s_nop 0
	v_mul_f32_e32 v9, 0x45800000, v56
	v_cndmask_b32_e32 v56, v56, v9, vcc
	v_accvgpr_read_b32 v9, a0
	v_accvgpr_read_b32 v54, a48
	v_accvgpr_read_b32 v55, a49
	v_lshlrev_b32_e32 v10, 16, v9
	v_and_b32_e32 v11, 0xffff0000, v9
	v_pk_mul_f32 v[10:11], v[10:11], v[54:55]
	v_accvgpr_read_b32 v9, a1
	v_accvgpr_read_b32 v54, a50
	v_accvgpr_read_b32 v55, a51
	v_lshlrev_b32_e32 v12, 16, v9
	v_and_b32_e32 v13, 0xffff0000, v9
	v_pk_mul_f32 v[12:13], v[12:13], v[54:55]
	v_accvgpr_read_b32 v9, a2
	v_accvgpr_read_b32 v54, a52
	v_accvgpr_read_b32 v55, a53
	v_lshlrev_b32_e32 v14, 16, v9
	v_and_b32_e32 v15, 0xffff0000, v9
	v_pk_mul_f32 v[14:15], v[14:15], v[54:55]
	v_accvgpr_read_b32 v9, a3
	v_accvgpr_read_b32 v54, a54
	v_accvgpr_read_b32 v55, a55
	v_lshlrev_b32_e32 v16, 16, v9
	v_and_b32_e32 v17, 0xffff0000, v9
	v_pk_mul_f32 v[16:17], v[16:17], v[54:55]
	v_accvgpr_read_b32 v9, a4
	v_accvgpr_read_b32 v54, a56
	v_accvgpr_read_b32 v55, a57
	v_lshlrev_b32_e32 v18, 16, v9
	v_and_b32_e32 v19, 0xffff0000, v9
	v_pk_mul_f32 v[18:19], v[18:19], v[54:55]
	v_accvgpr_read_b32 v9, a5
	v_accvgpr_read_b32 v54, a58
	v_accvgpr_read_b32 v55, a59
	v_lshlrev_b32_e32 v20, 16, v9
	v_and_b32_e32 v21, 0xffff0000, v9
	v_pk_mul_f32 v[20:21], v[20:21], v[54:55]
	v_accvgpr_read_b32 v9, a6
	v_accvgpr_read_b32 v54, a60
	v_accvgpr_read_b32 v55, a61
	v_lshlrev_b32_e32 v22, 16, v9
	v_and_b32_e32 v23, 0xffff0000, v9
	v_pk_mul_f32 v[22:23], v[22:23], v[54:55]
	v_accvgpr_read_b32 v9, a7
	v_accvgpr_read_b32 v54, a62
	v_accvgpr_read_b32 v55, a63
	v_lshlrev_b32_e32 v24, 16, v9
	v_and_b32_e32 v25, 0xffff0000, v9
	v_pk_mul_f32 v[24:25], v[24:25], v[54:55]
	v_cvt_pk_f32_fp8_e32 v[42:43], v60
	v_cvt_pk_f32_fp8_sdwa v[44:45], v60 src0_sel:WORD_1
	v_cvt_pk_f32_fp8_e32 v[46:47], v64
	v_cvt_pk_f32_fp8_sdwa v[48:49], v64 src0_sel:WORD_1
	v_pk_mul_f32 v[50:51], v[42:43], v[10:11]
	v_pk_mul_f32 v[52:53], v[46:47], v[10:11]
	v_pk_fma_f32 v[50:51], v[44:45], v[12:13], v[50:51]
	v_pk_fma_f32 v[52:53], v[48:49], v[12:13], v[52:53]
	v_cvt_pk_f32_fp8_e32 v[42:43], v61
	v_cvt_pk_f32_fp8_sdwa v[44:45], v61 src0_sel:WORD_1
	v_cvt_pk_f32_fp8_e32 v[46:47], v65
	v_cvt_pk_f32_fp8_sdwa v[48:49], v65 src0_sel:WORD_1
	v_pk_fma_f32 v[50:51], v[42:43], v[14:15], v[50:51]
	v_pk_fma_f32 v[52:53], v[46:47], v[14:15], v[52:53]
	v_pk_fma_f32 v[50:51], v[44:45], v[16:17], v[50:51]
	v_pk_fma_f32 v[52:53], v[48:49], v[16:17], v[52:53]
	v_cvt_pk_f32_fp8_e32 v[42:43], v62
	v_cvt_pk_f32_fp8_sdwa v[44:45], v62 src0_sel:WORD_1
	v_cvt_pk_f32_fp8_e32 v[46:47], v66
	v_cvt_pk_f32_fp8_sdwa v[48:49], v66 src0_sel:WORD_1
	v_pk_fma_f32 v[50:51], v[42:43], v[18:19], v[50:51]
	v_pk_fma_f32 v[52:53], v[46:47], v[18:19], v[52:53]
	v_pk_fma_f32 v[50:51], v[44:45], v[20:21], v[50:51]
	v_pk_fma_f32 v[52:53], v[48:49], v[20:21], v[52:53]
	v_cvt_pk_f32_fp8_e32 v[42:43], v63
	v_cvt_pk_f32_fp8_sdwa v[44:45], v63 src0_sel:WORD_1
	v_cvt_pk_f32_fp8_e32 v[46:47], v67
	v_cvt_pk_f32_fp8_sdwa v[48:49], v67 src0_sel:WORD_1
	v_pk_fma_f32 v[50:51], v[42:43], v[22:23], v[50:51]
	v_pk_fma_f32 v[52:53], v[46:47], v[22:23], v[52:53]
	v_pk_fma_f32 v[50:51], v[44:45], v[24:25], v[50:51]
	v_pk_fma_f32 v[52:53], v[48:49], v[24:25], v[52:53]
	v_add_f32_e32 v26, v50, v51
	v_add_f32_e32 v27, v52, v53
	v_cvt_pk_f32_fp8_e32 v[42:43], v68
	v_cvt_pk_f32_fp8_sdwa v[44:45], v68 src0_sel:WORD_1
	v_cvt_pk_f32_fp8_e32 v[46:47], v72
	v_cvt_pk_f32_fp8_sdwa v[48:49], v72 src0_sel:WORD_1
	v_pk_mul_f32 v[50:51], v[42:43], v[10:11]
	v_pk_mul_f32 v[52:53], v[46:47], v[10:11]
	v_pk_fma_f32 v[50:51], v[44:45], v[12:13], v[50:51]
	v_pk_fma_f32 v[52:53], v[48:49], v[12:13], v[52:53]
	v_cvt_pk_f32_fp8_e32 v[42:43], v69
	v_cvt_pk_f32_fp8_sdwa v[44:45], v69 src0_sel:WORD_1
	v_cvt_pk_f32_fp8_e32 v[46:47], v73
	v_cvt_pk_f32_fp8_sdwa v[48:49], v73 src0_sel:WORD_1
	v_pk_fma_f32 v[50:51], v[42:43], v[14:15], v[50:51]
	v_pk_fma_f32 v[52:53], v[46:47], v[14:15], v[52:53]
	v_pk_fma_f32 v[50:51], v[44:45], v[16:17], v[50:51]
	v_pk_fma_f32 v[52:53], v[48:49], v[16:17], v[52:53]
	v_cvt_pk_f32_fp8_e32 v[42:43], v70
	v_cvt_pk_f32_fp8_sdwa v[44:45], v70 src0_sel:WORD_1
	v_cvt_pk_f32_fp8_e32 v[46:47], v74
	v_cvt_pk_f32_fp8_sdwa v[48:49], v74 src0_sel:WORD_1
	v_pk_fma_f32 v[50:51], v[42:43], v[18:19], v[50:51]
	v_pk_fma_f32 v[52:53], v[46:47], v[18:19], v[52:53]
	v_pk_fma_f32 v[50:51], v[44:45], v[20:21], v[50:51]
	v_pk_fma_f32 v[52:53], v[48:49], v[20:21], v[52:53]
	v_cvt_pk_f32_fp8_e32 v[42:43], v71
	v_cvt_pk_f32_fp8_sdwa v[44:45], v71 src0_sel:WORD_1
	v_cvt_pk_f32_fp8_e32 v[46:47], v75
	v_cvt_pk_f32_fp8_sdwa v[48:49], v75 src0_sel:WORD_1
	v_pk_fma_f32 v[50:51], v[42:43], v[22:23], v[50:51]
	v_pk_fma_f32 v[52:53], v[46:47], v[22:23], v[52:53]
	v_pk_fma_f32 v[50:51], v[44:45], v[24:25], v[50:51]
	v_pk_fma_f32 v[52:53], v[48:49], v[24:25], v[52:53]
	v_add_f32_e32 v28, v50, v51
	v_add_f32_e32 v29, v52, v53
	v_cvt_pk_f32_fp8_e32 v[42:43], v76
	v_cvt_pk_f32_fp8_sdwa v[44:45], v76 src0_sel:WORD_1
	v_cvt_pk_f32_fp8_e32 v[46:47], v80
	v_cvt_pk_f32_fp8_sdwa v[48:49], v80 src0_sel:WORD_1
	v_pk_mul_f32 v[50:51], v[42:43], v[10:11]
	v_pk_mul_f32 v[52:53], v[46:47], v[10:11]
	v_pk_fma_f32 v[50:51], v[44:45], v[12:13], v[50:51]
	v_pk_fma_f32 v[52:53], v[48:49], v[12:13], v[52:53]
	v_cvt_pk_f32_fp8_e32 v[42:43], v77
	v_cvt_pk_f32_fp8_sdwa v[44:45], v77 src0_sel:WORD_1
	v_cvt_pk_f32_fp8_e32 v[46:47], v81
	v_cvt_pk_f32_fp8_sdwa v[48:49], v81 src0_sel:WORD_1
	v_pk_fma_f32 v[50:51], v[42:43], v[14:15], v[50:51]
	v_pk_fma_f32 v[52:53], v[46:47], v[14:15], v[52:53]
	v_pk_fma_f32 v[50:51], v[44:45], v[16:17], v[50:51]
	v_pk_fma_f32 v[52:53], v[48:49], v[16:17], v[52:53]
	v_cvt_pk_f32_fp8_e32 v[42:43], v78
	v_cvt_pk_f32_fp8_sdwa v[44:45], v78 src0_sel:WORD_1
	v_cvt_pk_f32_fp8_e32 v[46:47], v82
	v_cvt_pk_f32_fp8_sdwa v[48:49], v82 src0_sel:WORD_1
	v_pk_fma_f32 v[50:51], v[42:43], v[18:19], v[50:51]
	v_pk_fma_f32 v[52:53], v[46:47], v[18:19], v[52:53]
	v_pk_fma_f32 v[50:51], v[44:45], v[20:21], v[50:51]
	v_pk_fma_f32 v[52:53], v[48:49], v[20:21], v[52:53]
	v_cvt_pk_f32_fp8_e32 v[42:43], v79
	v_cvt_pk_f32_fp8_sdwa v[44:45], v79 src0_sel:WORD_1
	v_cvt_pk_f32_fp8_e32 v[46:47], v83
	v_cvt_pk_f32_fp8_sdwa v[48:49], v83 src0_sel:WORD_1
	v_pk_fma_f32 v[50:51], v[42:43], v[22:23], v[50:51]
	v_pk_fma_f32 v[52:53], v[46:47], v[22:23], v[52:53]
	v_pk_fma_f32 v[50:51], v[44:45], v[24:25], v[50:51]
	v_pk_fma_f32 v[52:53], v[48:49], v[24:25], v[52:53]
	v_add_f32_e32 v30, v50, v51
	v_add_f32_e32 v31, v52, v53
	v_cvt_pk_f32_fp8_e32 v[42:43], v84
	v_cvt_pk_f32_fp8_sdwa v[44:45], v84 src0_sel:WORD_1
	v_cvt_pk_f32_fp8_e32 v[46:47], v88
	v_cvt_pk_f32_fp8_sdwa v[48:49], v88 src0_sel:WORD_1
	v_pk_mul_f32 v[50:51], v[42:43], v[10:11]
	v_pk_mul_f32 v[52:53], v[46:47], v[10:11]
	v_pk_fma_f32 v[50:51], v[44:45], v[12:13], v[50:51]
	v_pk_fma_f32 v[52:53], v[48:49], v[12:13], v[52:53]
	v_cvt_pk_f32_fp8_e32 v[42:43], v85
	v_cvt_pk_f32_fp8_sdwa v[44:45], v85 src0_sel:WORD_1
	v_cvt_pk_f32_fp8_e32 v[46:47], v89
	v_cvt_pk_f32_fp8_sdwa v[48:49], v89 src0_sel:WORD_1
	v_pk_fma_f32 v[50:51], v[42:43], v[14:15], v[50:51]
	v_pk_fma_f32 v[52:53], v[46:47], v[14:15], v[52:53]
	v_pk_fma_f32 v[50:51], v[44:45], v[16:17], v[50:51]
	v_pk_fma_f32 v[52:53], v[48:49], v[16:17], v[52:53]
	v_cvt_pk_f32_fp8_e32 v[42:43], v86
	v_cvt_pk_f32_fp8_sdwa v[44:45], v86 src0_sel:WORD_1
	v_cvt_pk_f32_fp8_e32 v[46:47], v90
	v_cvt_pk_f32_fp8_sdwa v[48:49], v90 src0_sel:WORD_1
	v_pk_fma_f32 v[50:51], v[42:43], v[18:19], v[50:51]
	v_pk_fma_f32 v[52:53], v[46:47], v[18:19], v[52:53]
	v_pk_fma_f32 v[50:51], v[44:45], v[20:21], v[50:51]
	v_pk_fma_f32 v[52:53], v[48:49], v[20:21], v[52:53]
	v_cvt_pk_f32_fp8_e32 v[42:43], v87
	v_cvt_pk_f32_fp8_sdwa v[44:45], v87 src0_sel:WORD_1
	v_cvt_pk_f32_fp8_e32 v[46:47], v91
	v_cvt_pk_f32_fp8_sdwa v[48:49], v91 src0_sel:WORD_1
	v_pk_fma_f32 v[50:51], v[42:43], v[22:23], v[50:51]
	v_pk_fma_f32 v[52:53], v[46:47], v[22:23], v[52:53]
	v_pk_fma_f32 v[50:51], v[44:45], v[24:25], v[50:51]
	v_pk_fma_f32 v[52:53], v[48:49], v[24:25], v[52:53]
	v_add_f32_e32 v32, v50, v51
	v_add_f32_e32 v33, v52, v53
	v_cvt_pk_f32_fp8_e32 v[42:43], v92
	v_cvt_pk_f32_fp8_sdwa v[44:45], v92 src0_sel:WORD_1
	v_cvt_pk_f32_fp8_e32 v[46:47], v96
	v_cvt_pk_f32_fp8_sdwa v[48:49], v96 src0_sel:WORD_1
	v_pk_mul_f32 v[50:51], v[42:43], v[10:11]
	v_pk_mul_f32 v[52:53], v[46:47], v[10:11]
	v_pk_fma_f32 v[50:51], v[44:45], v[12:13], v[50:51]
	v_pk_fma_f32 v[52:53], v[48:49], v[12:13], v[52:53]
	v_cvt_pk_f32_fp8_e32 v[42:43], v93
	v_cvt_pk_f32_fp8_sdwa v[44:45], v93 src0_sel:WORD_1
	v_cvt_pk_f32_fp8_e32 v[46:47], v97
	v_cvt_pk_f32_fp8_sdwa v[48:49], v97 src0_sel:WORD_1
	v_pk_fma_f32 v[50:51], v[42:43], v[14:15], v[50:51]
	v_pk_fma_f32 v[52:53], v[46:47], v[14:15], v[52:53]
	v_pk_fma_f32 v[50:51], v[44:45], v[16:17], v[50:51]
	v_pk_fma_f32 v[52:53], v[48:49], v[16:17], v[52:53]
	v_cvt_pk_f32_fp8_e32 v[42:43], v94
	v_cvt_pk_f32_fp8_sdwa v[44:45], v94 src0_sel:WORD_1
	v_cvt_pk_f32_fp8_e32 v[46:47], v98
	v_cvt_pk_f32_fp8_sdwa v[48:49], v98 src0_sel:WORD_1
	v_pk_fma_f32 v[50:51], v[42:43], v[18:19], v[50:51]
	v_pk_fma_f32 v[52:53], v[46:47], v[18:19], v[52:53]
	v_pk_fma_f32 v[50:51], v[44:45], v[20:21], v[50:51]
	v_pk_fma_f32 v[52:53], v[48:49], v[20:21], v[52:53]
	v_cvt_pk_f32_fp8_e32 v[42:43], v95
	v_cvt_pk_f32_fp8_sdwa v[44:45], v95 src0_sel:WORD_1
	v_cvt_pk_f32_fp8_e32 v[46:47], v99
	v_cvt_pk_f32_fp8_sdwa v[48:49], v99 src0_sel:WORD_1
	v_pk_fma_f32 v[50:51], v[42:43], v[22:23], v[50:51]
	v_pk_fma_f32 v[52:53], v[46:47], v[22:23], v[52:53]
	v_pk_fma_f32 v[50:51], v[44:45], v[24:25], v[50:51]
	v_pk_fma_f32 v[52:53], v[48:49], v[24:25], v[52:53]
	v_add_f32_e32 v34, v50, v51
	v_add_f32_e32 v35, v52, v53
	v_cvt_pk_f32_fp8_e32 v[42:43], v100
	v_cvt_pk_f32_fp8_sdwa v[44:45], v100 src0_sel:WORD_1
	v_cvt_pk_f32_fp8_e32 v[46:47], v104
	v_cvt_pk_f32_fp8_sdwa v[48:49], v104 src0_sel:WORD_1
	v_pk_mul_f32 v[50:51], v[42:43], v[10:11]
	v_pk_mul_f32 v[52:53], v[46:47], v[10:11]
	v_pk_fma_f32 v[50:51], v[44:45], v[12:13], v[50:51]
	v_pk_fma_f32 v[52:53], v[48:49], v[12:13], v[52:53]
	v_cvt_pk_f32_fp8_e32 v[42:43], v101
	v_cvt_pk_f32_fp8_sdwa v[44:45], v101 src0_sel:WORD_1
	v_cvt_pk_f32_fp8_e32 v[46:47], v105
	v_cvt_pk_f32_fp8_sdwa v[48:49], v105 src0_sel:WORD_1
	v_pk_fma_f32 v[50:51], v[42:43], v[14:15], v[50:51]
	v_pk_fma_f32 v[52:53], v[46:47], v[14:15], v[52:53]
	v_pk_fma_f32 v[50:51], v[44:45], v[16:17], v[50:51]
	v_pk_fma_f32 v[52:53], v[48:49], v[16:17], v[52:53]
	v_cvt_pk_f32_fp8_e32 v[42:43], v102
	v_cvt_pk_f32_fp8_sdwa v[44:45], v102 src0_sel:WORD_1
	v_cvt_pk_f32_fp8_e32 v[46:47], v106
	v_cvt_pk_f32_fp8_sdwa v[48:49], v106 src0_sel:WORD_1
	v_pk_fma_f32 v[50:51], v[42:43], v[18:19], v[50:51]
	v_pk_fma_f32 v[52:53], v[46:47], v[18:19], v[52:53]
	v_pk_fma_f32 v[50:51], v[44:45], v[20:21], v[50:51]
	v_pk_fma_f32 v[52:53], v[48:49], v[20:21], v[52:53]
	v_cvt_pk_f32_fp8_e32 v[42:43], v103
	v_cvt_pk_f32_fp8_sdwa v[44:45], v103 src0_sel:WORD_1
	v_cvt_pk_f32_fp8_e32 v[46:47], v107
	v_cvt_pk_f32_fp8_sdwa v[48:49], v107 src0_sel:WORD_1
	v_pk_fma_f32 v[50:51], v[42:43], v[22:23], v[50:51]
	v_pk_fma_f32 v[52:53], v[46:47], v[22:23], v[52:53]
	v_pk_fma_f32 v[50:51], v[44:45], v[24:25], v[50:51]
	v_pk_fma_f32 v[52:53], v[48:49], v[24:25], v[52:53]
	v_add_f32_e32 v36, v50, v51
	v_add_f32_e32 v37, v52, v53
	v_cvt_pk_f32_fp8_e32 v[42:43], v108
	v_cvt_pk_f32_fp8_sdwa v[44:45], v108 src0_sel:WORD_1
	v_cvt_pk_f32_fp8_e32 v[46:47], v112
	v_cvt_pk_f32_fp8_sdwa v[48:49], v112 src0_sel:WORD_1
	v_pk_mul_f32 v[50:51], v[42:43], v[10:11]
	v_pk_mul_f32 v[52:53], v[46:47], v[10:11]
	v_pk_fma_f32 v[50:51], v[44:45], v[12:13], v[50:51]
	v_pk_fma_f32 v[52:53], v[48:49], v[12:13], v[52:53]
	v_cvt_pk_f32_fp8_e32 v[42:43], v109
	v_cvt_pk_f32_fp8_sdwa v[44:45], v109 src0_sel:WORD_1
	v_cvt_pk_f32_fp8_e32 v[46:47], v113
	v_cvt_pk_f32_fp8_sdwa v[48:49], v113 src0_sel:WORD_1
	v_pk_fma_f32 v[50:51], v[42:43], v[14:15], v[50:51]
	v_pk_fma_f32 v[52:53], v[46:47], v[14:15], v[52:53]
	v_pk_fma_f32 v[50:51], v[44:45], v[16:17], v[50:51]
	v_pk_fma_f32 v[52:53], v[48:49], v[16:17], v[52:53]
	v_cvt_pk_f32_fp8_e32 v[42:43], v110
	v_cvt_pk_f32_fp8_sdwa v[44:45], v110 src0_sel:WORD_1
	v_cvt_pk_f32_fp8_e32 v[46:47], v114
	v_cvt_pk_f32_fp8_sdwa v[48:49], v114 src0_sel:WORD_1
	v_pk_fma_f32 v[50:51], v[42:43], v[18:19], v[50:51]
	v_pk_fma_f32 v[52:53], v[46:47], v[18:19], v[52:53]
	v_pk_fma_f32 v[50:51], v[44:45], v[20:21], v[50:51]
	v_pk_fma_f32 v[52:53], v[48:49], v[20:21], v[52:53]
	v_cvt_pk_f32_fp8_e32 v[42:43], v111
	v_cvt_pk_f32_fp8_sdwa v[44:45], v111 src0_sel:WORD_1
	v_cvt_pk_f32_fp8_e32 v[46:47], v115
	v_cvt_pk_f32_fp8_sdwa v[48:49], v115 src0_sel:WORD_1
	v_pk_fma_f32 v[50:51], v[42:43], v[22:23], v[50:51]
	v_pk_fma_f32 v[52:53], v[46:47], v[22:23], v[52:53]
	v_pk_fma_f32 v[50:51], v[44:45], v[24:25], v[50:51]
	v_pk_fma_f32 v[52:53], v[48:49], v[24:25], v[52:53]
	v_add_f32_e32 v38, v50, v51
	v_add_f32_e32 v39, v52, v53
	v_cvt_pk_f32_fp8_e32 v[42:43], v116
	v_cvt_pk_f32_fp8_sdwa v[44:45], v116 src0_sel:WORD_1
	v_cvt_pk_f32_fp8_e32 v[46:47], v120
	v_cvt_pk_f32_fp8_sdwa v[48:49], v120 src0_sel:WORD_1
	v_pk_mul_f32 v[50:51], v[42:43], v[10:11]
	v_pk_mul_f32 v[52:53], v[46:47], v[10:11]
	v_pk_fma_f32 v[50:51], v[44:45], v[12:13], v[50:51]
	v_pk_fma_f32 v[52:53], v[48:49], v[12:13], v[52:53]
	v_cvt_pk_f32_fp8_e32 v[42:43], v117
	v_cvt_pk_f32_fp8_sdwa v[44:45], v117 src0_sel:WORD_1
	v_cvt_pk_f32_fp8_e32 v[46:47], v121
	v_cvt_pk_f32_fp8_sdwa v[48:49], v121 src0_sel:WORD_1
	v_pk_fma_f32 v[50:51], v[42:43], v[14:15], v[50:51]
	v_pk_fma_f32 v[52:53], v[46:47], v[14:15], v[52:53]
	v_pk_fma_f32 v[50:51], v[44:45], v[16:17], v[50:51]
	v_pk_fma_f32 v[52:53], v[48:49], v[16:17], v[52:53]
	v_cvt_pk_f32_fp8_e32 v[42:43], v118
	v_cvt_pk_f32_fp8_sdwa v[44:45], v118 src0_sel:WORD_1
	v_cvt_pk_f32_fp8_e32 v[46:47], v122
	v_cvt_pk_f32_fp8_sdwa v[48:49], v122 src0_sel:WORD_1
	v_pk_fma_f32 v[50:51], v[42:43], v[18:19], v[50:51]
	v_pk_fma_f32 v[52:53], v[46:47], v[18:19], v[52:53]
	v_pk_fma_f32 v[50:51], v[44:45], v[20:21], v[50:51]
	v_pk_fma_f32 v[52:53], v[48:49], v[20:21], v[52:53]
	v_cvt_pk_f32_fp8_e32 v[42:43], v119
	v_cvt_pk_f32_fp8_sdwa v[44:45], v119 src0_sel:WORD_1
	v_cvt_pk_f32_fp8_e32 v[46:47], v123
	v_cvt_pk_f32_fp8_sdwa v[48:49], v123 src0_sel:WORD_1
	v_pk_fma_f32 v[50:51], v[42:43], v[22:23], v[50:51]
	v_pk_fma_f32 v[52:53], v[46:47], v[22:23], v[52:53]
	v_pk_fma_f32 v[50:51], v[44:45], v[24:25], v[50:51]
	v_pk_fma_f32 v[52:53], v[48:49], v[24:25], v[52:53]
	v_add_f32_e32 v40, v50, v51
	v_add_f32_e32 v41, v52, v53
	s_lshl_b32 s11, s12, 12
	v_add_u32_e32 v6, s11, v3
	v_add_f32_dpp v42, v26, v26 row_half_mirror row_mask:0xf bank_mask:0xf
	v_add_f32_dpp v43, v34, v34 row_half_mirror row_mask:0xf bank_mask:0xf
	v_cndmask_b32_e64 v26, v42, v43, s[14:15]
	v_add_f32_dpp v44, v27, v27 row_half_mirror row_mask:0xf bank_mask:0xf
	v_add_f32_dpp v45, v35, v35 row_half_mirror row_mask:0xf bank_mask:0xf
	v_cndmask_b32_e64 v27, v44, v45, s[14:15]
	v_add_f32_dpp v42, v28, v28 row_half_mirror row_mask:0xf bank_mask:0xf
	v_add_f32_dpp v43, v36, v36 row_half_mirror row_mask:0xf bank_mask:0xf
	v_cndmask_b32_e64 v28, v42, v43, s[14:15]
	v_add_f32_dpp v44, v29, v29 row_half_mirror row_mask:0xf bank_mask:0xf
	v_add_f32_dpp v45, v37, v37 row_half_mirror row_mask:0xf bank_mask:0xf
	v_cndmask_b32_e64 v29, v44, v45, s[14:15]
	v_add_f32_dpp v42, v30, v30 row_half_mirror row_mask:0xf bank_mask:0xf
	v_add_f32_dpp v43, v38, v38 row_half_mirror row_mask:0xf bank_mask:0xf
	v_cndmask_b32_e64 v30, v42, v43, s[14:15]
	v_add_f32_dpp v44, v31, v31 row_half_mirror row_mask:0xf bank_mask:0xf
	v_add_f32_dpp v45, v39, v39 row_half_mirror row_mask:0xf bank_mask:0xf
	v_cndmask_b32_e64 v31, v44, v45, s[14:15]
	v_add_f32_dpp v42, v32, v32 row_half_mirror row_mask:0xf bank_mask:0xf
	v_add_f32_dpp v43, v40, v40 row_half_mirror row_mask:0xf bank_mask:0xf
	v_cndmask_b32_e64 v32, v42, v43, s[14:15]
	v_add_f32_dpp v44, v33, v33 row_half_mirror row_mask:0xf bank_mask:0xf
	v_add_f32_dpp v45, v41, v41 row_half_mirror row_mask:0xf bank_mask:0xf
	v_cndmask_b32_e64 v33, v44, v45, s[14:15]
	s_nop 1
	v_add_f32_dpp v42, v26, v26 quad_perm:[2,3,0,1] row_mask:0xf bank_mask:0xf
	v_add_f32_dpp v43, v30, v30 quad_perm:[2,3,0,1] row_mask:0xf bank_mask:0xf
	v_cndmask_b32_e64 v26, v42, v43, s[40:41]
	v_add_f32_dpp v44, v27, v27 quad_perm:[2,3,0,1] row_mask:0xf bank_mask:0xf
	v_add_f32_dpp v45, v31, v31 quad_perm:[2,3,0,1] row_mask:0xf bank_mask:0xf
	v_cndmask_b32_e64 v27, v44, v45, s[40:41]
	v_add_f32_dpp v42, v28, v28 quad_perm:[2,3,0,1] row_mask:0xf bank_mask:0xf
	v_add_f32_dpp v43, v32, v32 quad_perm:[2,3,0,1] row_mask:0xf bank_mask:0xf
	v_cndmask_b32_e64 v28, v42, v43, s[40:41]
	v_add_f32_dpp v44, v29, v29 quad_perm:[2,3,0,1] row_mask:0xf bank_mask:0xf
	v_add_f32_dpp v45, v33, v33 quad_perm:[2,3,0,1] row_mask:0xf bank_mask:0xf
	v_cndmask_b32_e64 v29, v44, v45, s[40:41]
	s_nop 1
	v_add_f32_dpp v42, v26, v26 quad_perm:[1,0,3,2] row_mask:0xf bank_mask:0xf
	v_add_f32_dpp v43, v28, v28 quad_perm:[1,0,3,2] row_mask:0xf bank_mask:0xf
	v_cndmask_b32_e64 v26, v42, v43, s[42:43]
	v_add_f32_dpp v44, v27, v27 quad_perm:[1,0,3,2] row_mask:0xf bank_mask:0xf
	v_add_f32_dpp v45, v29, v29 quad_perm:[1,0,3,2] row_mask:0xf bank_mask:0xf
	v_cndmask_b32_e64 v27, v44, v45, s[42:43]
	s_nop 1
	v_mul_f32_e32 v26, v26, v56
	v_mul_f32_e32 v27, v27, v56
	global_store_dwordx2 v6, v[26:27], s[6:7]
.Lp5u_skip0:
	s_add_u32 s10, s8, s26
	s_min_u32 s10, s10, s13
	s_lshl_b32 s18, s10, 10
	s_add_u32 s11, s16, 7
	s_and_b32 s11, s11, 7
	s_lshl_b32 s11, s11, 10
	s_add_u32 s11, s11, s17
	s_mov_b32 m0, s11
	v_lshl_add_u64 v[4:5], v[58:59], 0, s[18:19]
	global_load_lds_dwordx4 v[4:5], off
	s_add_u32 s11, s16, 3
	s_and_b32 s11, s11, 7
	s_lshl_b32 s11, s11, 10
	v_add_u32_e32 v8, s11, v2
	ds_read_b128 v[10:13], v8 offset:0
	ds_read_b128 v[14:17], v8 offset:16
	ds_read_b128 v[18:21], v8 offset:32
	ds_read_b128 v[22:25], v8 offset:48
	s_add_u32 s10, s8, s22
	s_min_u32 s10, s10, s13
	s_lshl_b32 s11, s10, 11
	v_add_u32_e32 v6, s11, v7
	global_load_dwordx4 a[0:3], v6, s[36:37]
	global_load_dwordx4 a[4:7], v6, s[36:37] offset:16
	s_lshl_b32 s11, s10, 2
	v_mov_b32_e32 v6, s11
	global_load_dword a8, v6, s[38:39]
	s_waitcnt lgkmcnt(0)
	v_add_u32_e32 v10, v10, v1
	global_load_dwordx4 v[60:63], v10, s[2:3]
	v_add_u32_e32 v11, v11, v1
	global_load_dwordx4 v[64:67], v11, s[2:3]
	v_add_u32_e32 v12, v12, v1
	global_load_dwordx4 v[68:71], v12, s[2:3]
	v_add_u32_e32 v13, v13, v1
	global_load_dwordx4 v[72:75], v13, s[2:3]
	v_add_u32_e32 v14, v14, v1
	global_load_dwordx4 v[76:79], v14, s[2:3]
	v_add_u32_e32 v15, v15, v1
	global_load_dwordx4 v[80:83], v15, s[2:3]
	v_add_u32_e32 v16, v16, v1
	global_load_dwordx4 v[84:87], v16, s[2:3]
	v_add_u32_e32 v17, v17, v1
	global_load_dwordx4 v[88:91], v17, s[2:3]
	v_add_u32_e32 v18, v18, v1
	global_load_dwordx4 v[92:95], v18, s[2:3]
	v_add_u32_e32 v19, v19, v1
	global_load_dwordx4 v[96:99], v19, s[2:3]
	v_add_u32_e32 v20, v20, v1
	global_load_dwordx4 v[100:103], v20, s[2:3]
	v_add_u32_e32 v21, v21, v1
	global_load_dwordx4 v[104:107], v21, s[2:3]
	v_add_u32_e32 v22, v22, v1
	global_load_dwordx4 v[108:111], v22, s[2:3]
	v_add_u32_e32 v23, v23, v1
	global_load_dwordx4 v[112:115], v23, s[2:3]
	v_add_u32_e32 v24, v24, v1
	global_load_dwordx4 v[116:119], v24, s[2:3]
	v_add_u32_e32 v25, v25, v1
	global_load_dwordx4 v[120:123], v25, s[2:3]
	s_add_u32 s12, s8, s20
	s_waitcnt vmcnt(42)
	s_cmp_lt_u32 s12, 0x4200
	s_cbranch_scc0 .Lp5u_skip1
; __device__ __forceinline__ float bflo(unsigned u) { return __uint_as_float(u << 16); }
; __device__ __forceinline__ float bfhi(unsigned u) { return __uint_as_float(u & 0xffff0000u); }
; __device__ __forceinline__ void phase5(const Params& p, char* smem, const bool store_x = true) {
;     ...
;     float2v h2[8];
;     {
;       const uint4 a = cur_ha;
;       const uint4 b2 = cur_hb;
;       h2[0] = float2v{bflo(a.x), bfhi(a.x)}; h2[1] = float2v{bflo(a.y), bfhi(a.y)}; h2[2] = float2v{bflo(a.z), bfhi(a.z)}; h2[3] = float2v{bflo(a.w), bfhi(a.w)};
;       h2[4] = float2v{bflo(b2.x), bfhi(b2.x)}; h2[5] = float2v{bflo(b2.y), bfhi(b2.y)}; h2[6] = float2v{bflo(b2.z), bfhi(b2.z)}; h2[7] = float2v{bflo(b2.w), bfhi(b2.w)};
; #pragma unroll
;       for (int i = 0; i < 8; i++) h2[i] = h2[i] * gf[i] * cur_rs;
;     }
	v_accvgpr_read_b32 v56, a24
	v_fmamk_f32 v56, v56, 0x3a800000, v57
	v_mul_f32_e32 v9, 0x4b800000, v56
	v_cmp_gt_f32_e32 vcc, s33, v56
	s_nop 1
	v_cndmask_b32_e32 v56, v56, v9, vcc
	v_rsq_f32_e32 v56, v56
	s_nop 0
	v_mul_f32_e32 v9, 0x45800000, v56
	v_cndmask_b32_e32 v56, v56, v9, vcc
	v_accvgpr_read_b32 v9, a16
	v_accvgpr_read_b32 v54, a48
	v_accvgpr_read_b32 v55, a49
	v_lshlrev_b32_e32 v10, 16, v9
	v_and_b32_e32 v11, 0xffff0000, v9
	v_pk_mul_f32 v[10:11], v[10:11], v[54:55]
	v_accvgpr_read_b32 v9, a17
	v_accvgpr_read_b32 v54, a50
	v_accvgpr_read_b32 v55, a51
	v_lshlrev_b32_e32 v12, 16, v9
	v_and_b32_e32 v13, 0xffff0000, v9
	v_pk_mul_f32 v[12:13], v[12:13], v[54:55]
	v_accvgpr_read_b32 v9, a18
	v_accvgpr_read_b32 v54, a52
	v_accvgpr_read_b32 v55, a53
	v_lshlrev_b32_e32 v14, 16, v9
	v_and_b32_e32 v15, 0xffff0000, v9
	v_pk_mul_f32 v[14:15], v[14:15], v[54:55]
	v_accvgpr_read_b32 v9, a19
	v_accvgpr_read_b32 v54, a54
	v_accvgpr_read_b32 v55, a55
	v_lshlrev_b32_e32 v16, 16, v9
	v_and_b32_e32 v17, 0xffff0000, v9
	v_pk_mul_f32 v[16:17], v[16:17], v[54:55]
	v_accvgpr_read_b32 v9, a20
	v_accvgpr_read_b32 v54, a56
	v_accvgpr_read_b32 v55, a57
	v_lshlrev_b32_e32 v18, 16, v9
	v_and_b32_e32 v19, 0xffff0000, v9
	v_pk_mul_f32 v[18:19], v[18:19], v[54:55]
	v_accvgpr_read_b32 v9, a21
	v_accvgpr_read_b32 v54, a58
	v_accvgpr_read_b32 v55, a59
	v_lshlrev_b32_e32 v20, 16, v9
	v_and_b32_e32 v21, 0xffff0000, v9
	v_pk_mul_f32 v[20:21], v[20:21], v[54:55]
	v_accvgpr_read_b32 v9, a22
	v_accvgpr_read_b32 v54, a60
	v_accvgpr_read_b32 v55, a61
	v_lshlrev_b32_e32 v22, 16, v9
	v_and_b32_e32 v23, 0xffff0000, v9
	v_pk_mul_f32 v[22:23], v[22:23], v[54:55]
	v_accvgpr_read_b32 v9, a23
	v_accvgpr_read_b32 v54, a62
	v_accvgpr_read_b32 v55, a63
	v_lshlrev_b32_e32 v24, 16, v9
	v_and_b32_e32 v25, 0xffff0000, v9
	v_pk_mul_f32 v[24:25], v[24:25], v[54:55]
	v_cvt_pk_f32_fp8_e32 v[42:43], v124
	v_cvt_pk_f32_fp8_sdwa v[44:45], v124 src0_sel:WORD_1
	v_cvt_pk_f32_fp8_e32 v[46:47], v128
	v_cvt_pk_f32_fp8_sdwa v[48:49], v128 src0_sel:WORD_1
	v_pk_mul_f32 v[50:51], v[42:43], v[10:11]
	v_pk_mul_f32 v[52:53], v[46:47], v[10:11]
	v_pk_fma_f32 v[50:51], v[44:45], v[12:13], v[50:51]
	v_pk_fma_f32 v[52:53], v[48:49], v[12:13], v[52:53]
	v_cvt_pk_f32_fp8_e32 v[42:43], v125
	v_cvt_pk_f32_fp8_sdwa v[44:45], v125 src0_sel:WORD_1
	v_cvt_pk_f32_fp8_e32 v[46:47], v129
	v_cvt_pk_f32_fp8_sdwa v[48:49], v129 src0_sel:WORD_1
	v_pk_fma_f32 v[50:51], v[42:43], v[14:15], v[50:51]
	v_pk_fma_f32 v[52:53], v[46:47], v[14:15], v[52:53]
	v_pk_fma_f32 v[50:51], v[44:45], v[16:17], v[50:51]
	v_pk_fma_f32 v[52:53], v[48:49], v[16:17], v[52:53]
	v_cvt_pk_f32_fp8_e32 v[42:43], v126
	v_cvt_pk_f32_fp8_sdwa v[44:45], v126 src0_sel:WORD_1
	v_cvt_pk_f32_fp8_e32 v[46:47], v130
	v_cvt_pk_f32_fp8_sdwa v[48:49], v130 src0_sel:WORD_1
	v_pk_fma_f32 v[50:51], v[42:43], v[18:19], v[50:51]
	v_pk_fma_f32 v[52:53], v[46:47], v[18:19], v[52:53]
	v_pk_fma_f32 v[50:51], v[44:45], v[20:21], v[50:51]
	v_pk_fma_f32 v[52:53], v[48:49], v[20:21], v[52:53]
	v_cvt_pk_f32_fp8_e32 v[42:43], v127
	v_cvt_pk_f32_fp8_sdwa v[44:45], v127 src0_sel:WORD_1
	v_cvt_pk_f32_fp8_e32 v[46:47], v131
	v_cvt_pk_f32_fp8_sdwa v[48:49], v131 src0_sel:WORD_1
	v_pk_fma_f32 v[50:51], v[42:43], v[22:23], v[50:51]
	v_pk_fma_f32 v[52:53], v[46:47], v[22:23], v[52:53]
	v_pk_fma_f32 v[50:51], v[44:45], v[24:25], v[50:51]
	v_pk_fma_f32 v[52:53], v[48:49], v[24:25], v[52:53]
	v_add_f32_e32 v26, v50, v51
	v_add_f32_e32 v27, v52, v53
	v_cvt_pk_f32_fp8_e32 v[42:43], v132
	v_cvt_pk_f32_fp8_sdwa v[44:45], v132 src0_sel:WORD_1
	v_cvt_pk_f32_fp8_e32 v[46:47], v136
	v_cvt_pk_f32_fp8_sdwa v[48:49], v136 src0_sel:WORD_1
	v_pk_mul_f32 v[50:51], v[42:43], v[10:11]
	v_pk_mul_f32 v[52:53], v[46:47], v[10:11]
	v_pk_fma_f32 v[50:51], v[44:45], v[12:13], v[50:51]
	v_pk_fma_f32 v[52:53], v[48:49], v[12:13], v[52:53]
	v_cvt_pk_f32_fp8_e32 v[42:43], v133
	v_cvt_pk_f32_fp8_sdwa v[44:45], v133 src0_sel:WORD_1
	v_cvt_pk_f32_fp8_e32 v[46:47], v137
	v_cvt_pk_f32_fp8_sdwa v[48:49], v137 src0_sel:WORD_1
	v_pk_fma_f32 v[50:51], v[42:43], v[14:15], v[50:51]
	v_pk_fma_f32 v[52:53], v[46:47], v[14:15], v[52:53]
	v_pk_fma_f32 v[50:51], v[44:45], v[16:17], v[50:51]
	v_pk_fma_f32 v[52:53], v[48:49], v[16:17], v[52:53]
	v_cvt_pk_f32_fp8_e32 v[42:43], v134
	v_cvt_pk_f32_fp8_sdwa v[44:45], v134 src0_sel:WORD_1
	v_cvt_pk_f32_fp8_e32 v[46:47], v138
	v_cvt_pk_f32_fp8_sdwa v[48:49], v138 src0_sel:WORD_1
	v_pk_fma_f32 v[50:51], v[42:43], v[18:19], v[50:51]
	v_pk_fma_f32 v[52:53], v[46:47], v[18:19], v[52:53]
	v_pk_fma_f32 v[50:51], v[44:45], v[20:21], v[50:51]
	v_pk_fma_f32 v[52:53], v[48:49], v[20:21], v[52:53]
	v_cvt_pk_f32_fp8_e32 v[42:43], v135
	v_cvt_pk_f32_fp8_sdwa v[44:45], v135 src0_sel:WORD_1
	v_cvt_pk_f32_fp8_e32 v[46:47], v139
	v_cvt_pk_f32_fp8_sdwa v[48:49], v139 src0_sel:WORD_1
	v_pk_fma_f32 v[50:51], v[42:43], v[22:23], v[50:51]
	v_pk_fma_f32 v[52:53], v[46:47], v[22:23], v[52:53]
	v_pk_fma_f32 v[50:51], v[44:45], v[24:25], v[50:51]
	v_pk_fma_f32 v[52:53], v[48:49], v[24:25], v[52:53]
	v_add_f32_e32 v28, v50, v51
	v_add_f32_e32 v29, v52, v53
	v_cvt_pk_f32_fp8_e32 v[42:43], v140
	v_cvt_pk_f32_fp8_sdwa v[44:45], v140 src0_sel:WORD_1
	v_cvt_pk_f32_fp8_e32 v[46:47], v144
	v_cvt_pk_f32_fp8_sdwa v[48:49], v144 src0_sel:WORD_1
	v_pk_mul_f32 v[50:51], v[42:43], v[10:11]
	v_pk_mul_f32 v[52:53], v[46:47], v[10:11]
	v_pk_fma_f32 v[50:51], v[44:45], v[12:13], v[50:51]
	v_pk_fma_f32 v[52:53], v[48:49], v[12:13], v[52:53]
	v_cvt_pk_f32_fp8_e32 v[42:43], v141
	v_cvt_pk_f32_fp8_sdwa v[44:45], v141 src0_sel:WORD_1
	v_cvt_pk_f32_fp8_e32 v[46:47], v145
	v_cvt_pk_f32_fp8_sdwa v[48:49], v145 src0_sel:WORD_1
	v_pk_fma_f32 v[50:51], v[42:43], v[14:15], v[50:51]
	v_pk_fma_f32 v[52:53], v[46:47], v[14:15], v[52:53]
	v_pk_fma_f32 v[50:51], v[44:45], v[16:17], v[50:51]
	v_pk_fma_f32 v[52:53], v[48:49], v[16:17], v[52:53]
	v_cvt_pk_f32_fp8_e32 v[42:43], v142
	v_cvt_pk_f32_fp8_sdwa v[44:45], v142 src0_sel:WORD_1
	v_cvt_pk_f32_fp8_e32 v[46:47], v146
	v_cvt_pk_f32_fp8_sdwa v[48:49], v146 src0_sel:WORD_1
	v_pk_fma_f32 v[50:51], v[42:43], v[18:19], v[50:51]
	v_pk_fma_f32 v[52:53], v[46:47], v[18:19], v[52:53]
	v_pk_fma_f32 v[50:51], v[44:45], v[20:21], v[50:51]
	v_pk_fma_f32 v[52:53], v[48:49], v[20:21], v[52:53]
	v_cvt_pk_f32_fp8_e32 v[42:43], v143
	v_cvt_pk_f32_fp8_sdwa v[44:45], v143 src0_sel:WORD_1
	v_cvt_pk_f32_fp8_e32 v[46:47], v147
	v_cvt_pk_f32_fp8_sdwa v[48:49], v147 src0_sel:WORD_1
	v_pk_fma_f32 v[50:51], v[42:43], v[22:23], v[50:51]
	v_pk_fma_f32 v[52:53], v[46:47], v[22:23], v[52:53]
	v_pk_fma_f32 v[50:51], v[44:45], v[24:25], v[50:51]
	v_pk_fma_f32 v[52:53], v[48:49], v[24:25], v[52:53]
	v_add_f32_e32 v30, v50, v51
	v_add_f32_e32 v31, v52, v53
	v_cvt_pk_f32_fp8_e32 v[42:43], v148
	v_cvt_pk_f32_fp8_sdwa v[44:45], v148 src0_sel:WORD_1
	v_cvt_pk_f32_fp8_e32 v[46:47], v152
	v_cvt_pk_f32_fp8_sdwa v[48:49], v152 src0_sel:WORD_1
	v_pk_mul_f32 v[50:51], v[42:43], v[10:11]
	v_pk_mul_f32 v[52:53], v[46:47], v[10:11]
	v_pk_fma_f32 v[50:51], v[44:45], v[12:13], v[50:51]
	v_pk_fma_f32 v[52:53], v[48:49], v[12:13], v[52:53]
	v_cvt_pk_f32_fp8_e32 v[42:43], v149
	v_cvt_pk_f32_fp8_sdwa v[44:45], v149 src0_sel:WORD_1
	v_cvt_pk_f32_fp8_e32 v[46:47], v153
	v_cvt_pk_f32_fp8_sdwa v[48:49], v153 src0_sel:WORD_1
	v_pk_fma_f32 v[50:51], v[42:43], v[14:15], v[50:51]
	v_pk_fma_f32 v[52:53], v[46:47], v[14:15], v[52:53]
	v_pk_fma_f32 v[50:51], v[44:45], v[16:17], v[50:51]
	v_pk_fma_f32 v[52:53], v[48:49], v[16:17], v[52:53]
	v_cvt_pk_f32_fp8_e32 v[42:43], v150
	v_cvt_pk_f32_fp8_sdwa v[44:45], v150 src0_sel:WORD_1
	v_cvt_pk_f32_fp8_e32 v[46:47], v154
	v_cvt_pk_f32_fp8_sdwa v[48:49], v154 src0_sel:WORD_1
	v_pk_fma_f32 v[50:51], v[42:43], v[18:19], v[50:51]
	v_pk_fma_f32 v[52:53], v[46:47], v[18:19], v[52:53]
	v_pk_fma_f32 v[50:51], v[44:45], v[20:21], v[50:51]
	v_pk_fma_f32 v[52:53], v[48:49], v[20:21], v[52:53]
	v_cvt_pk_f32_fp8_e32 v[42:43], v151
	v_cvt_pk_f32_fp8_sdwa v[44:45], v151 src0_sel:WORD_1
	v_cvt_pk_f32_fp8_e32 v[46:47], v155
	v_cvt_pk_f32_fp8_sdwa v[48:49], v155 src0_sel:WORD_1
	v_pk_fma_f32 v[50:51], v[42:43], v[22:23], v[50:51]
	v_pk_fma_f32 v[52:53], v[46:47], v[22:23], v[52:53]
	v_pk_fma_f32 v[50:51], v[44:45], v[24:25], v[50:51]
	v_pk_fma_f32 v[52:53], v[48:49], v[24:25], v[52:53]
	v_add_f32_e32 v32, v50, v51
	v_add_f32_e32 v33, v52, v53
	v_cvt_pk_f32_fp8_e32 v[42:43], v156
	v_cvt_pk_f32_fp8_sdwa v[44:45], v156 src0_sel:WORD_1
	v_cvt_pk_f32_fp8_e32 v[46:47], v160
	v_cvt_pk_f32_fp8_sdwa v[48:49], v160 src0_sel:WORD_1
	v_pk_mul_f32 v[50:51], v[42:43], v[10:11]
	v_pk_mul_f32 v[52:53], v[46:47], v[10:11]
	v_pk_fma_f32 v[50:51], v[44:45], v[12:13], v[50:51]
	v_pk_fma_f32 v[52:53], v[48:49], v[12:13], v[52:53]
	v_cvt_pk_f32_fp8_e32 v[42:43], v157
	v_cvt_pk_f32_fp8_sdwa v[44:45], v157 src0_sel:WORD_1
	v_cvt_pk_f32_fp8_e32 v[46:47], v161
	v_cvt_pk_f32_fp8_sdwa v[48:49], v161 src0_sel:WORD_1
	v_pk_fma_f32 v[50:51], v[42:43], v[14:15], v[50:51]
	v_pk_fma_f32 v[52:53], v[46:47], v[14:15], v[52:53]
	v_pk_fma_f32 v[50:51], v[44:45], v[16:17], v[50:51]
	v_pk_fma_f32 v[52:53], v[48:49], v[16:17], v[52:53]
	v_cvt_pk_f32_fp8_e32 v[42:43], v158
	v_cvt_pk_f32_fp8_sdwa v[44:45], v158 src0_sel:WORD_1
	v_cvt_pk_f32_fp8_e32 v[46:47], v162
	v_cvt_pk_f32_fp8_sdwa v[48:49], v162 src0_sel:WORD_1
	v_pk_fma_f32 v[50:51], v[42:43], v[18:19], v[50:51]
	v_pk_fma_f32 v[52:53], v[46:47], v[18:19], v[52:53]
	v_pk_fma_f32 v[50:51], v[44:45], v[20:21], v[50:51]
	v_pk_fma_f32 v[52:53], v[48:49], v[20:21], v[52:53]
	v_cvt_pk_f32_fp8_e32 v[42:43], v159
	v_cvt_pk_f32_fp8_sdwa v[44:45], v159 src0_sel:WORD_1
	v_cvt_pk_f32_fp8_e32 v[46:47], v163
	v_cvt_pk_f32_fp8_sdwa v[48:49], v163 src0_sel:WORD_1
	v_pk_fma_f32 v[50:51], v[42:43], v[22:23], v[50:51]
	v_pk_fma_f32 v[52:53], v[46:47], v[22:23], v[52:53]
	v_pk_fma_f32 v[50:51], v[44:45], v[24:25], v[50:51]
	v_pk_fma_f32 v[52:53], v[48:49], v[24:25], v[52:53]
	v_add_f32_e32 v34, v50, v51
	v_add_f32_e32 v35, v52, v53
	v_cvt_pk_f32_fp8_e32 v[42:43], v164
	v_cvt_pk_f32_fp8_sdwa v[44:45], v164 src0_sel:WORD_1
	v_cvt_pk_f32_fp8_e32 v[46:47], v168
	v_cvt_pk_f32_fp8_sdwa v[48:49], v168 src0_sel:WORD_1
	v_pk_mul_f32 v[50:51], v[42:43], v[10:11]
	v_pk_mul_f32 v[52:53], v[46:47], v[10:11]
	v_pk_fma_f32 v[50:51], v[44:45], v[12:13], v[50:51]
	v_pk_fma_f32 v[52:53], v[48:49], v[12:13], v[52:53]
	v_cvt_pk_f32_fp8_e32 v[42:43], v165
	v_cvt_pk_f32_fp8_sdwa v[44:45], v165 src0_sel:WORD_1
	v_cvt_pk_f32_fp8_e32 v[46:47], v169
	v_cvt_pk_f32_fp8_sdwa v[48:49], v169 src0_sel:WORD_1
	v_pk_fma_f32 v[50:51], v[42:43], v[14:15], v[50:51]
	v_pk_fma_f32 v[52:53], v[46:47], v[14:15], v[52:53]
	v_pk_fma_f32 v[50:51], v[44:45], v[16:17], v[50:51]
	v_pk_fma_f32 v[52:53], v[48:49], v[16:17], v[52:53]
	v_cvt_pk_f32_fp8_e32 v[42:43], v166
	v_cvt_pk_f32_fp8_sdwa v[44:45], v166 src0_sel:WORD_1
	v_cvt_pk_f32_fp8_e32 v[46:47], v170
	v_cvt_pk_f32_fp8_sdwa v[48:49], v170 src0_sel:WORD_1
	v_pk_fma_f32 v[50:51], v[42:43], v[18:19], v[50:51]
	v_pk_fma_f32 v[52:53], v[46:47], v[18:19], v[52:53]
	v_pk_fma_f32 v[50:51], v[44:45], v[20:21], v[50:51]
	v_pk_fma_f32 v[52:53], v[48:49], v[20:21], v[52:53]
	v_cvt_pk_f32_fp8_e32 v[42:43], v167
	v_cvt_pk_f32_fp8_sdwa v[44:45], v167 src0_sel:WORD_1
	v_cvt_pk_f32_fp8_e32 v[46:47], v171
	v_cvt_pk_f32_fp8_sdwa v[48:49], v171 src0_sel:WORD_1
	v_pk_fma_f32 v[50:51], v[42:43], v[22:23], v[50:51]
	v_pk_fma_f32 v[52:53], v[46:47], v[22:23], v[52:53]
	v_pk_fma_f32 v[50:51], v[44:45], v[24:25], v[50:51]
	v_pk_fma_f32 v[52:53], v[48:49], v[24:25], v[52:53]
	v_add_f32_e32 v36, v50, v51
	v_add_f32_e32 v37, v52, v53
	v_cvt_pk_f32_fp8_e32 v[42:43], v172
	v_cvt_pk_f32_fp8_sdwa v[44:45], v172 src0_sel:WORD_1
	v_cvt_pk_f32_fp8_e32 v[46:47], v176
	v_cvt_pk_f32_fp8_sdwa v[48:49], v176 src0_sel:WORD_1
	v_pk_mul_f32 v[50:51], v[42:43], v[10:11]
	v_pk_mul_f32 v[52:53], v[46:47], v[10:11]
	v_pk_fma_f32 v[50:51], v[44:45], v[12:13], v[50:51]
	v_pk_fma_f32 v[52:53], v[48:49], v[12:13], v[52:53]
	v_cvt_pk_f32_fp8_e32 v[42:43], v173
	v_cvt_pk_f32_fp8_sdwa v[44:45], v173 src0_sel:WORD_1
	v_cvt_pk_f32_fp8_e32 v[46:47], v177
	v_cvt_pk_f32_fp8_sdwa v[48:49], v177 src0_sel:WORD_1
	v_pk_fma_f32 v[50:51], v[42:43], v[14:15], v[50:51]
	v_pk_fma_f32 v[52:53], v[46:47], v[14:15], v[52:53]
	v_pk_fma_f32 v[50:51], v[44:45], v[16:17], v[50:51]
	v_pk_fma_f32 v[52:53], v[48:49], v[16:17], v[52:53]
	v_cvt_pk_f32_fp8_e32 v[42:43], v174
	v_cvt_pk_f32_fp8_sdwa v[44:45], v174 src0_sel:WORD_1
	v_cvt_pk_f32_fp8_e32 v[46:47], v178
	v_cvt_pk_f32_fp8_sdwa v[48:49], v178 src0_sel:WORD_1
	v_pk_fma_f32 v[50:51], v[42:43], v[18:19], v[50:51]
	v_pk_fma_f32 v[52:53], v[46:47], v[18:19], v[52:53]
	v_pk_fma_f32 v[50:51], v[44:45], v[20:21], v[50:51]
	v_pk_fma_f32 v[52:53], v[48:49], v[20:21], v[52:53]
	v_cvt_pk_f32_fp8_e32 v[42:43], v175
	v_cvt_pk_f32_fp8_sdwa v[44:45], v175 src0_sel:WORD_1
	v_cvt_pk_f32_fp8_e32 v[46:47], v179
	v_cvt_pk_f32_fp8_sdwa v[48:49], v179 src0_sel:WORD_1
	v_pk_fma_f32 v[50:51], v[42:43], v[22:23], v[50:51]
	v_pk_fma_f32 v[52:53], v[46:47], v[22:23], v[52:53]
	v_pk_fma_f32 v[50:51], v[44:45], v[24:25], v[50:51]
	v_pk_fma_f32 v[52:53], v[48:49], v[24:25], v[52:53]
	v_add_f32_e32 v38, v50, v51
	v_add_f32_e32 v39, v52, v53
	v_cvt_pk_f32_fp8_e32 v[42:43], v180
	v_cvt_pk_f32_fp8_sdwa v[44:45], v180 src0_sel:WORD_1
	v_cvt_pk_f32_fp8_e32 v[46:47], v184
	v_cvt_pk_f32_fp8_sdwa v[48:49], v184 src0_sel:WORD_1
	v_pk_mul_f32 v[50:51], v[42:43], v[10:11]
	v_pk_mul_f32 v[52:53], v[46:47], v[10:11]
	v_pk_fma_f32 v[50:51], v[44:45], v[12:13], v[50:51]
	v_pk_fma_f32 v[52:53], v[48:49], v[12:13], v[52:53]
	v_cvt_pk_f32_fp8_e32 v[42:43], v181
	v_cvt_pk_f32_fp8_sdwa v[44:45], v181 src0_sel:WORD_1
	v_cvt_pk_f32_fp8_e32 v[46:47], v185
	v_cvt_pk_f32_fp8_sdwa v[48:49], v185 src0_sel:WORD_1
	v_pk_fma_f32 v[50:51], v[42:43], v[14:15], v[50:51]
	v_pk_fma_f32 v[52:53], v[46:47], v[14:15], v[52:53]
	v_pk_fma_f32 v[50:51], v[44:45], v[16:17], v[50:51]
	v_pk_fma_f32 v[52:53], v[48:49], v[16:17], v[52:53]
	v_cvt_pk_f32_fp8_e32 v[42:43], v182
	v_cvt_pk_f32_fp8_sdwa v[44:45], v182 src0_sel:WORD_1
	v_cvt_pk_f32_fp8_e32 v[46:47], v186
	v_cvt_pk_f32_fp8_sdwa v[48:49], v186 src0_sel:WORD_1
	v_pk_fma_f32 v[50:51], v[42:43], v[18:19], v[50:51]
	v_pk_fma_f32 v[52:53], v[46:47], v[18:19], v[52:53]
	v_pk_fma_f32 v[50:51], v[44:45], v[20:21], v[50:51]
	v_pk_fma_f32 v[52:53], v[48:49], v[20:21], v[52:53]
	v_cvt_pk_f32_fp8_e32 v[42:43], v183
	v_cvt_pk_f32_fp8_sdwa v[44:45], v183 src0_sel:WORD_1
	v_cvt_pk_f32_fp8_e32 v[46:47], v187
	v_cvt_pk_f32_fp8_sdwa v[48:49], v187 src0_sel:WORD_1
	v_pk_fma_f32 v[50:51], v[42:43], v[22:23], v[50:51]
	v_pk_fma_f32 v[52:53], v[46:47], v[22:23], v[52:53]
	v_pk_fma_f32 v[50:51], v[44:45], v[24:25], v[50:51]
	v_pk_fma_f32 v[52:53], v[48:49], v[24:25], v[52:53]
	v_add_f32_e32 v40, v50, v51
	v_add_f32_e32 v41, v52, v53
	s_lshl_b32 s11, s12, 12
	v_add_u32_e32 v6, s11, v3
	v_add_f32_dpp v42, v26, v26 row_half_mirror row_mask:0xf bank_mask:0xf
	v_add_f32_dpp v43, v34, v34 row_half_mirror row_mask:0xf bank_mask:0xf
	v_cndmask_b32_e64 v26, v42, v43, s[14:15]
	v_add_f32_dpp v44, v27, v27 row_half_mirror row_mask:0xf bank_mask:0xf
	v_add_f32_dpp v45, v35, v35 row_half_mirror row_mask:0xf bank_mask:0xf
	v_cndmask_b32_e64 v27, v44, v45, s[14:15]
	v_add_f32_dpp v42, v28, v28 row_half_mirror row_mask:0xf bank_mask:0xf
	v_add_f32_dpp v43, v36, v36 row_half_mirror row_mask:0xf bank_mask:0xf
	v_cndmask_b32_e64 v28, v42, v43, s[14:15]
	v_add_f32_dpp v44, v29, v29 row_half_mirror row_mask:0xf bank_mask:0xf
	v_add_f32_dpp v45, v37, v37 row_half_mirror row_mask:0xf bank_mask:0xf
	v_cndmask_b32_e64 v29, v44, v45, s[14:15]
	v_add_f32_dpp v42, v30, v30 row_half_mirror row_mask:0xf bank_mask:0xf
	v_add_f32_dpp v43, v38, v38 row_half_mirror row_mask:0xf bank_mask:0xf
	v_cndmask_b32_e64 v30, v42, v43, s[14:15]
	v_add_f32_dpp v44, v31, v31 row_half_mirror row_mask:0xf bank_mask:0xf
	v_add_f32_dpp v45, v39, v39 row_half_mirror row_mask:0xf bank_mask:0xf
	v_cndmask_b32_e64 v31, v44, v45, s[14:15]
	v_add_f32_dpp v42, v32, v32 row_half_mirror row_mask:0xf bank_mask:0xf
	v_add_f32_dpp v43, v40, v40 row_half_mirror row_mask:0xf bank_mask:0xf
	v_cndmask_b32_e64 v32, v42, v43, s[14:15]
	v_add_f32_dpp v44, v33, v33 row_half_mirror row_mask:0xf bank_mask:0xf
	v_add_f32_dpp v45, v41, v41 row_half_mirror row_mask:0xf bank_mask:0xf
	v_cndmask_b32_e64 v33, v44, v45, s[14:15]
	s_nop 1
	v_add_f32_dpp v42, v26, v26 quad_perm:[2,3,0,1] row_mask:0xf bank_mask:0xf
	v_add_f32_dpp v43, v30, v30 quad_perm:[2,3,0,1] row_mask:0xf bank_mask:0xf
	v_cndmask_b32_e64 v26, v42, v43, s[40:41]
	v_add_f32_dpp v44, v27, v27 quad_perm:[2,3,0,1] row_mask:0xf bank_mask:0xf
	v_add_f32_dpp v45, v31, v31 quad_perm:[2,3,0,1] row_mask:0xf bank_mask:0xf
	v_cndmask_b32_e64 v27, v44, v45, s[40:41]
	v_add_f32_dpp v42, v28, v28 quad_perm:[2,3,0,1] row_mask:0xf bank_mask:0xf
	v_add_f32_dpp v43, v32, v32 quad_perm:[2,3,0,1] row_mask:0xf bank_mask:0xf
	v_cndmask_b32_e64 v28, v42, v43, s[40:41]
	v_add_f32_dpp v44, v29, v29 quad_perm:[2,3,0,1] row_mask:0xf bank_mask:0xf
	v_add_f32_dpp v45, v33, v33 quad_perm:[2,3,0,1] row_mask:0xf bank_mask:0xf
	v_cndmask_b32_e64 v29, v44, v45, s[40:41]
	s_nop 1
	v_add_f32_dpp v42, v26, v26 quad_perm:[1,0,3,2] row_mask:0xf bank_mask:0xf
	v_add_f32_dpp v43, v28, v28 quad_perm:[1,0,3,2] row_mask:0xf bank_mask:0xf
	v_cndmask_b32_e64 v26, v42, v43, s[42:43]
	v_add_f32_dpp v44, v27, v27 quad_perm:[1,0,3,2] row_mask:0xf bank_mask:0xf
	v_add_f32_dpp v45, v29, v29 quad_perm:[1,0,3,2] row_mask:0xf bank_mask:0xf
	v_cndmask_b32_e64 v27, v44, v45, s[42:43]
	s_nop 1
	v_mul_f32_e32 v26, v26, v56
	v_mul_f32_e32 v27, v27, v56
	global_store_dwordx2 v6, v[26:27], s[6:7]
.Lp5u_skip1:
	s_add_u32 s10, s8, s27
	s_min_u32 s10, s10, s13
	s_lshl_b32 s18, s10, 10
	s_add_u32 s11, s16, 8
	s_and_b32 s11, s11, 7
	s_lshl_b32 s11, s11, 10
	s_add_u32 s11, s11, s17
	s_mov_b32 m0, s11
	v_lshl_add_u64 v[4:5], v[58:59], 0, s[18:19]
	global_load_lds_dwordx4 v[4:5], off
	s_add_u32 s11, s16, 4
	s_and_b32 s11, s11, 7
	s_lshl_b32 s11, s11, 10
	v_add_u32_e32 v8, s11, v2
	ds_read_b128 v[10:13], v8 offset:0
	ds_read_b128 v[14:17], v8 offset:16
	ds_read_b128 v[18:21], v8 offset:32
	ds_read_b128 v[22:25], v8 offset:48
	s_add_u32 s10, s8, s23
	s_min_u32 s10, s10, s13
	s_lshl_b32 s11, s10, 11
	v_add_u32_e32 v6, s11, v7
	global_load_dwordx4 a[16:19], v6, s[36:37]
	global_load_dwordx4 a[20:23], v6, s[36:37] offset:16
	s_lshl_b32 s11, s10, 2
	v_mov_b32_e32 v6, s11
	global_load_dword a24, v6, s[38:39]
	s_waitcnt lgkmcnt(0)
	v_add_u32_e32 v10, v10, v1
	global_load_dwordx4 v[124:127], v10, s[2:3]
	v_add_u32_e32 v11, v11, v1
	global_load_dwordx4 v[128:131], v11, s[2:3]
	v_add_u32_e32 v12, v12, v1
	global_load_dwordx4 v[132:135], v12, s[2:3]
	v_add_u32_e32 v13, v13, v1
	global_load_dwordx4 v[136:139], v13, s[2:3]
	v_add_u32_e32 v14, v14, v1
	global_load_dwordx4 v[140:143], v14, s[2:3]
	v_add_u32_e32 v15, v15, v1
	global_load_dwordx4 v[144:147], v15, s[2:3]
	v_add_u32_e32 v16, v16, v1
	global_load_dwordx4 v[148:151], v16, s[2:3]
	v_add_u32_e32 v17, v17, v1
	global_load_dwordx4 v[152:155], v17, s[2:3]
	v_add_u32_e32 v18, v18, v1
	global_load_dwordx4 v[156:159], v18, s[2:3]
	v_add_u32_e32 v19, v19, v1
	global_load_dwordx4 v[160:163], v19, s[2:3]
	v_add_u32_e32 v20, v20, v1
	global_load_dwordx4 v[164:167], v20, s[2:3]
	v_add_u32_e32 v21, v21, v1
	global_load_dwordx4 v[168:171], v21, s[2:3]
	v_add_u32_e32 v22, v22, v1
	global_load_dwordx4 v[172:175], v22, s[2:3]
	v_add_u32_e32 v23, v23, v1
	global_load_dwordx4 v[176:179], v23, s[2:3]
	v_add_u32_e32 v24, v24, v1
	global_load_dwordx4 v[180:183], v24, s[2:3]
	v_add_u32_e32 v25, v25, v1
	global_load_dwordx4 v[184:187], v25, s[2:3]
	s_add_u32 s12, s8, s21
	s_waitcnt vmcnt(42)
	s_cmp_lt_u32 s12, 0x4200
	s_cbranch_scc0 .Lp5u_skip2
	v_accvgpr_read_b32 v56, a40
	v_fmamk_f32 v56, v56, 0x3a800000, v57
	v_mul_f32_e32 v9, 0x4b800000, v56
	v_cmp_gt_f32_e32 vcc, s33, v56
	s_nop 1
	v_cndmask_b32_e32 v56, v56, v9, vcc
	v_rsq_f32_e32 v56, v56
	s_nop 0
	v_mul_f32_e32 v9, 0x45800000, v56
	v_cndmask_b32_e32 v56, v56, v9, vcc
	v_accvgpr_read_b32 v9, a32
	v_accvgpr_read_b32 v54, a48
	v_accvgpr_read_b32 v55, a49
	v_lshlrev_b32_e32 v10, 16, v9
	v_and_b32_e32 v11, 0xffff0000, v9
	v_pk_mul_f32 v[10:11], v[10:11], v[54:55]
	v_accvgpr_read_b32 v9, a33
	v_accvgpr_read_b32 v54, a50
	v_accvgpr_read_b32 v55, a51
	v_lshlrev_b32_e32 v12, 16, v9
	v_and_b32_e32 v13, 0xffff0000, v9
	v_pk_mul_f32 v[12:13], v[12:13], v[54:55]
	v_accvgpr_read_b32 v9, a34
	v_accvgpr_read_b32 v54, a52
	v_accvgpr_read_b32 v55, a53
	v_lshlrev_b32_e32 v14, 16, v9
	v_and_b32_e32 v15, 0xffff0000, v9
	v_pk_mul_f32 v[14:15], v[14:15], v[54:55]
	v_accvgpr_read_b32 v9, a35
	v_accvgpr_read_b32 v54, a54
	v_accvgpr_read_b32 v55, a55
	v_lshlrev_b32_e32 v16, 16, v9
	v_and_b32_e32 v17, 0xffff0000, v9
	v_pk_mul_f32 v[16:17], v[16:17], v[54:55]
	v_accvgpr_read_b32 v9, a36
	v_accvgpr_read_b32 v54, a56
	v_accvgpr_read_b32 v55, a57
	v_lshlrev_b32_e32 v18, 16, v9
	v_and_b32_e32 v19, 0xffff0000, v9
	v_pk_mul_f32 v[18:19], v[18:19], v[54:55]
	v_accvgpr_read_b32 v9, a37
	v_accvgpr_read_b32 v54, a58
	v_accvgpr_read_b32 v55, a59
	v_lshlrev_b32_e32 v20, 16, v9
	v_and_b32_e32 v21, 0xffff0000, v9
	v_pk_mul_f32 v[20:21], v[20:21], v[54:55]
	v_accvgpr_read_b32 v9, a38
	v_accvgpr_read_b32 v54, a60
	v_accvgpr_read_b32 v55, a61
	v_lshlrev_b32_e32 v22, 16, v9
	v_and_b32_e32 v23, 0xffff0000, v9
	v_pk_mul_f32 v[22:23], v[22:23], v[54:55]
	v_accvgpr_read_b32 v9, a39
	v_accvgpr_read_b32 v54, a62
	v_accvgpr_read_b32 v55, a63
	v_lshlrev_b32_e32 v24, 16, v9
	v_and_b32_e32 v25, 0xffff0000, v9
	v_pk_mul_f32 v[24:25], v[24:25], v[54:55]
	v_cvt_pk_f32_fp8_e32 v[42:43], v188
	v_cvt_pk_f32_fp8_sdwa v[44:45], v188 src0_sel:WORD_1
	v_cvt_pk_f32_fp8_e32 v[46:47], v192
	v_cvt_pk_f32_fp8_sdwa v[48:49], v192 src0_sel:WORD_1
	v_pk_mul_f32 v[50:51], v[42:43], v[10:11]
	v_pk_mul_f32 v[52:53], v[46:47], v[10:11]
	v_pk_fma_f32 v[50:51], v[44:45], v[12:13], v[50:51]
	v_pk_fma_f32 v[52:53], v[48:49], v[12:13], v[52:53]
	v_cvt_pk_f32_fp8_e32 v[42:43], v189
	v_cvt_pk_f32_fp8_sdwa v[44:45], v189 src0_sel:WORD_1
	v_cvt_pk_f32_fp8_e32 v[46:47], v193
	v_cvt_pk_f32_fp8_sdwa v[48:49], v193 src0_sel:WORD_1
	v_pk_fma_f32 v[50:51], v[42:43], v[14:15], v[50:51]
	v_pk_fma_f32 v[52:53], v[46:47], v[14:15], v[52:53]
	v_pk_fma_f32 v[50:51], v[44:45], v[16:17], v[50:51]
	v_pk_fma_f32 v[52:53], v[48:49], v[16:17], v[52:53]
	v_cvt_pk_f32_fp8_e32 v[42:43], v190
	v_cvt_pk_f32_fp8_sdwa v[44:45], v190 src0_sel:WORD_1
	v_cvt_pk_f32_fp8_e32 v[46:47], v194
	v_cvt_pk_f32_fp8_sdwa v[48:49], v194 src0_sel:WORD_1
	v_pk_fma_f32 v[50:51], v[42:43], v[18:19], v[50:51]
	v_pk_fma_f32 v[52:53], v[46:47], v[18:19], v[52:53]
	v_pk_fma_f32 v[50:51], v[44:45], v[20:21], v[50:51]
	v_pk_fma_f32 v[52:53], v[48:49], v[20:21], v[52:53]
	v_cvt_pk_f32_fp8_e32 v[42:43], v191
	v_cvt_pk_f32_fp8_sdwa v[44:45], v191 src0_sel:WORD_1
	v_cvt_pk_f32_fp8_e32 v[46:47], v195
	v_cvt_pk_f32_fp8_sdwa v[48:49], v195 src0_sel:WORD_1
	v_pk_fma_f32 v[50:51], v[42:43], v[22:23], v[50:51]
	v_pk_fma_f32 v[52:53], v[46:47], v[22:23], v[52:53]
	v_pk_fma_f32 v[50:51], v[44:45], v[24:25], v[50:51]
	v_pk_fma_f32 v[52:53], v[48:49], v[24:25], v[52:53]
	v_add_f32_e32 v26, v50, v51
	v_add_f32_e32 v27, v52, v53
	v_cvt_pk_f32_fp8_e32 v[42:43], v196
	v_cvt_pk_f32_fp8_sdwa v[44:45], v196 src0_sel:WORD_1
	v_cvt_pk_f32_fp8_e32 v[46:47], v200
	v_cvt_pk_f32_fp8_sdwa v[48:49], v200 src0_sel:WORD_1
	v_pk_mul_f32 v[50:51], v[42:43], v[10:11]
	v_pk_mul_f32 v[52:53], v[46:47], v[10:11]
	v_pk_fma_f32 v[50:51], v[44:45], v[12:13], v[50:51]
	v_pk_fma_f32 v[52:53], v[48:49], v[12:13], v[52:53]
	v_cvt_pk_f32_fp8_e32 v[42:43], v197
	v_cvt_pk_f32_fp8_sdwa v[44:45], v197 src0_sel:WORD_1
	v_cvt_pk_f32_fp8_e32 v[46:47], v201
	v_cvt_pk_f32_fp8_sdwa v[48:49], v201 src0_sel:WORD_1
	v_pk_fma_f32 v[50:51], v[42:43], v[14:15], v[50:51]
	v_pk_fma_f32 v[52:53], v[46:47], v[14:15], v[52:53]
	v_pk_fma_f32 v[50:51], v[44:45], v[16:17], v[50:51]
	v_pk_fma_f32 v[52:53], v[48:49], v[16:17], v[52:53]
	v_cvt_pk_f32_fp8_e32 v[42:43], v198
	v_cvt_pk_f32_fp8_sdwa v[44:45], v198 src0_sel:WORD_1
	v_cvt_pk_f32_fp8_e32 v[46:47], v202
	v_cvt_pk_f32_fp8_sdwa v[48:49], v202 src0_sel:WORD_1
	v_pk_fma_f32 v[50:51], v[42:43], v[18:19], v[50:51]
	v_pk_fma_f32 v[52:53], v[46:47], v[18:19], v[52:53]
	v_pk_fma_f32 v[50:51], v[44:45], v[20:21], v[50:51]
	v_pk_fma_f32 v[52:53], v[48:49], v[20:21], v[52:53]
	v_cvt_pk_f32_fp8_e32 v[42:43], v199
	v_cvt_pk_f32_fp8_sdwa v[44:45], v199 src0_sel:WORD_1
	v_cvt_pk_f32_fp8_e32 v[46:47], v203
	v_cvt_pk_f32_fp8_sdwa v[48:49], v203 src0_sel:WORD_1
	v_pk_fma_f32 v[50:51], v[42:43], v[22:23], v[50:51]
	v_pk_fma_f32 v[52:53], v[46:47], v[22:23], v[52:53]
	v_pk_fma_f32 v[50:51], v[44:45], v[24:25], v[50:51]
	v_pk_fma_f32 v[52:53], v[48:49], v[24:25], v[52:53]
	v_add_f32_e32 v28, v50, v51
	v_add_f32_e32 v29, v52, v53
	v_cvt_pk_f32_fp8_e32 v[42:43], v204
	v_cvt_pk_f32_fp8_sdwa v[44:45], v204 src0_sel:WORD_1
	v_cvt_pk_f32_fp8_e32 v[46:47], v208
	v_cvt_pk_f32_fp8_sdwa v[48:49], v208 src0_sel:WORD_1
	v_pk_mul_f32 v[50:51], v[42:43], v[10:11]
	v_pk_mul_f32 v[52:53], v[46:47], v[10:11]
	v_pk_fma_f32 v[50:51], v[44:45], v[12:13], v[50:51]
	v_pk_fma_f32 v[52:53], v[48:49], v[12:13], v[52:53]
	v_cvt_pk_f32_fp8_e32 v[42:43], v205
	v_cvt_pk_f32_fp8_sdwa v[44:45], v205 src0_sel:WORD_1
	v_cvt_pk_f32_fp8_e32 v[46:47], v209
	v_cvt_pk_f32_fp8_sdwa v[48:49], v209 src0_sel:WORD_1
	v_pk_fma_f32 v[50:51], v[42:43], v[14:15], v[50:51]
	v_pk_fma_f32 v[52:53], v[46:47], v[14:15], v[52:53]
	v_pk_fma_f32 v[50:51], v[44:45], v[16:17], v[50:51]
	v_pk_fma_f32 v[52:53], v[48:49], v[16:17], v[52:53]
	v_cvt_pk_f32_fp8_e32 v[42:43], v206
	v_cvt_pk_f32_fp8_sdwa v[44:45], v206 src0_sel:WORD_1
	v_cvt_pk_f32_fp8_e32 v[46:47], v210
	v_cvt_pk_f32_fp8_sdwa v[48:49], v210 src0_sel:WORD_1
	v_pk_fma_f32 v[50:51], v[42:43], v[18:19], v[50:51]
	v_pk_fma_f32 v[52:53], v[46:47], v[18:19], v[52:53]
	v_pk_fma_f32 v[50:51], v[44:45], v[20:21], v[50:51]
	v_pk_fma_f32 v[52:53], v[48:49], v[20:21], v[52:53]
	v_cvt_pk_f32_fp8_e32 v[42:43], v207
	v_cvt_pk_f32_fp8_sdwa v[44:45], v207 src0_sel:WORD_1
	v_cvt_pk_f32_fp8_e32 v[46:47], v211
	v_cvt_pk_f32_fp8_sdwa v[48:49], v211 src0_sel:WORD_1
	v_pk_fma_f32 v[50:51], v[42:43], v[22:23], v[50:51]
	v_pk_fma_f32 v[52:53], v[46:47], v[22:23], v[52:53]
	v_pk_fma_f32 v[50:51], v[44:45], v[24:25], v[50:51]
	v_pk_fma_f32 v[52:53], v[48:49], v[24:25], v[52:53]
	v_add_f32_e32 v30, v50, v51
	v_add_f32_e32 v31, v52, v53
	v_cvt_pk_f32_fp8_e32 v[42:43], v212
	v_cvt_pk_f32_fp8_sdwa v[44:45], v212 src0_sel:WORD_1
	v_cvt_pk_f32_fp8_e32 v[46:47], v216
	v_cvt_pk_f32_fp8_sdwa v[48:49], v216 src0_sel:WORD_1
	v_pk_mul_f32 v[50:51], v[42:43], v[10:11]
	v_pk_mul_f32 v[52:53], v[46:47], v[10:11]
	v_pk_fma_f32 v[50:51], v[44:45], v[12:13], v[50:51]
	v_pk_fma_f32 v[52:53], v[48:49], v[12:13], v[52:53]
	v_cvt_pk_f32_fp8_e32 v[42:43], v213
	v_cvt_pk_f32_fp8_sdwa v[44:45], v213 src0_sel:WORD_1
	v_cvt_pk_f32_fp8_e32 v[46:47], v217
	v_cvt_pk_f32_fp8_sdwa v[48:49], v217 src0_sel:WORD_1
	v_pk_fma_f32 v[50:51], v[42:43], v[14:15], v[50:51]
	v_pk_fma_f32 v[52:53], v[46:47], v[14:15], v[52:53]
	v_pk_fma_f32 v[50:51], v[44:45], v[16:17], v[50:51]
	v_pk_fma_f32 v[52:53], v[48:49], v[16:17], v[52:53]
	v_cvt_pk_f32_fp8_e32 v[42:43], v214
	v_cvt_pk_f32_fp8_sdwa v[44:45], v214 src0_sel:WORD_1
	v_cvt_pk_f32_fp8_e32 v[46:47], v218
	v_cvt_pk_f32_fp8_sdwa v[48:49], v218 src0_sel:WORD_1
	v_pk_fma_f32 v[50:51], v[42:43], v[18:19], v[50:51]
	v_pk_fma_f32 v[52:53], v[46:47], v[18:19], v[52:53]
	v_pk_fma_f32 v[50:51], v[44:45], v[20:21], v[50:51]
	v_pk_fma_f32 v[52:53], v[48:49], v[20:21], v[52:53]
	v_cvt_pk_f32_fp8_e32 v[42:43], v215
	v_cvt_pk_f32_fp8_sdwa v[44:45], v215 src0_sel:WORD_1
	v_cvt_pk_f32_fp8_e32 v[46:47], v219
	v_cvt_pk_f32_fp8_sdwa v[48:49], v219 src0_sel:WORD_1
	v_pk_fma_f32 v[50:51], v[42:43], v[22:23], v[50:51]
	v_pk_fma_f32 v[52:53], v[46:47], v[22:23], v[52:53]
	v_pk_fma_f32 v[50:51], v[44:45], v[24:25], v[50:51]
	v_pk_fma_f32 v[52:53], v[48:49], v[24:25], v[52:53]
	v_add_f32_e32 v32, v50, v51
	v_add_f32_e32 v33, v52, v53
	v_cvt_pk_f32_fp8_e32 v[42:43], v220
	v_cvt_pk_f32_fp8_sdwa v[44:45], v220 src0_sel:WORD_1
	v_cvt_pk_f32_fp8_e32 v[46:47], v224
	v_cvt_pk_f32_fp8_sdwa v[48:49], v224 src0_sel:WORD_1
	v_pk_mul_f32 v[50:51], v[42:43], v[10:11]
	v_pk_mul_f32 v[52:53], v[46:47], v[10:11]
	v_pk_fma_f32 v[50:51], v[44:45], v[12:13], v[50:51]
	v_pk_fma_f32 v[52:53], v[48:49], v[12:13], v[52:53]
	v_cvt_pk_f32_fp8_e32 v[42:43], v221
	v_cvt_pk_f32_fp8_sdwa v[44:45], v221 src0_sel:WORD_1
	v_cvt_pk_f32_fp8_e32 v[46:47], v225
	v_cvt_pk_f32_fp8_sdwa v[48:49], v225 src0_sel:WORD_1
	v_pk_fma_f32 v[50:51], v[42:43], v[14:15], v[50:51]
	v_pk_fma_f32 v[52:53], v[46:47], v[14:15], v[52:53]
	v_pk_fma_f32 v[50:51], v[44:45], v[16:17], v[50:51]
	v_pk_fma_f32 v[52:53], v[48:49], v[16:17], v[52:53]
	v_cvt_pk_f32_fp8_e32 v[42:43], v222
	v_cvt_pk_f32_fp8_sdwa v[44:45], v222 src0_sel:WORD_1
	v_cvt_pk_f32_fp8_e32 v[46:47], v226
	v_cvt_pk_f32_fp8_sdwa v[48:49], v226 src0_sel:WORD_1
	v_pk_fma_f32 v[50:51], v[42:43], v[18:19], v[50:51]
	v_pk_fma_f32 v[52:53], v[46:47], v[18:19], v[52:53]
	v_pk_fma_f32 v[50:51], v[44:45], v[20:21], v[50:51]
	v_pk_fma_f32 v[52:53], v[48:49], v[20:21], v[52:53]
	v_cvt_pk_f32_fp8_e32 v[42:43], v223
	v_cvt_pk_f32_fp8_sdwa v[44:45], v223 src0_sel:WORD_1
	v_cvt_pk_f32_fp8_e32 v[46:47], v227
	v_cvt_pk_f32_fp8_sdwa v[48:49], v227 src0_sel:WORD_1
	v_pk_fma_f32 v[50:51], v[42:43], v[22:23], v[50:51]
	v_pk_fma_f32 v[52:53], v[46:47], v[22:23], v[52:53]
	v_pk_fma_f32 v[50:51], v[44:45], v[24:25], v[50:51]
	v_pk_fma_f32 v[52:53], v[48:49], v[24:25], v[52:53]
	v_add_f32_e32 v34, v50, v51
	v_add_f32_e32 v35, v52, v53
	v_cvt_pk_f32_fp8_e32 v[42:43], v228
	v_cvt_pk_f32_fp8_sdwa v[44:45], v228 src0_sel:WORD_1
	v_cvt_pk_f32_fp8_e32 v[46:47], v232
	v_cvt_pk_f32_fp8_sdwa v[48:49], v232 src0_sel:WORD_1
	v_pk_mul_f32 v[50:51], v[42:43], v[10:11]
	v_pk_mul_f32 v[52:53], v[46:47], v[10:11]
	v_pk_fma_f32 v[50:51], v[44:45], v[12:13], v[50:51]
	v_pk_fma_f32 v[52:53], v[48:49], v[12:13], v[52:53]
	v_cvt_pk_f32_fp8_e32 v[42:43], v229
	v_cvt_pk_f32_fp8_sdwa v[44:45], v229 src0_sel:WORD_1
	v_cvt_pk_f32_fp8_e32 v[46:47], v233
	v_cvt_pk_f32_fp8_sdwa v[48:49], v233 src0_sel:WORD_1
	v_pk_fma_f32 v[50:51], v[42:43], v[14:15], v[50:51]
	v_pk_fma_f32 v[52:53], v[46:47], v[14:15], v[52:53]
	v_pk_fma_f32 v[50:51], v[44:45], v[16:17], v[50:51]
	v_pk_fma_f32 v[52:53], v[48:49], v[16:17], v[52:53]
	v_cvt_pk_f32_fp8_e32 v[42:43], v230
	v_cvt_pk_f32_fp8_sdwa v[44:45], v230 src0_sel:WORD_1
	v_cvt_pk_f32_fp8_e32 v[46:47], v234
	v_cvt_pk_f32_fp8_sdwa v[48:49], v234 src0_sel:WORD_1
	v_pk_fma_f32 v[50:51], v[42:43], v[18:19], v[50:51]
	v_pk_fma_f32 v[52:53], v[46:47], v[18:19], v[52:53]
	v_pk_fma_f32 v[50:51], v[44:45], v[20:21], v[50:51]
	v_pk_fma_f32 v[52:53], v[48:49], v[20:21], v[52:53]
	v_cvt_pk_f32_fp8_e32 v[42:43], v231
	v_cvt_pk_f32_fp8_sdwa v[44:45], v231 src0_sel:WORD_1
	v_cvt_pk_f32_fp8_e32 v[46:47], v235
	v_cvt_pk_f32_fp8_sdwa v[48:49], v235 src0_sel:WORD_1
	v_pk_fma_f32 v[50:51], v[42:43], v[22:23], v[50:51]
	v_pk_fma_f32 v[52:53], v[46:47], v[22:23], v[52:53]
	v_pk_fma_f32 v[50:51], v[44:45], v[24:25], v[50:51]
	v_pk_fma_f32 v[52:53], v[48:49], v[24:25], v[52:53]
	v_add_f32_e32 v36, v50, v51
	v_add_f32_e32 v37, v52, v53
	v_cvt_pk_f32_fp8_e32 v[42:43], v236
	v_cvt_pk_f32_fp8_sdwa v[44:45], v236 src0_sel:WORD_1
	v_cvt_pk_f32_fp8_e32 v[46:47], v240
	v_cvt_pk_f32_fp8_sdwa v[48:49], v240 src0_sel:WORD_1
	v_pk_mul_f32 v[50:51], v[42:43], v[10:11]
	v_pk_mul_f32 v[52:53], v[46:47], v[10:11]
	v_pk_fma_f32 v[50:51], v[44:45], v[12:13], v[50:51]
	v_pk_fma_f32 v[52:53], v[48:49], v[12:13], v[52:53]
	v_cvt_pk_f32_fp8_e32 v[42:43], v237
	v_cvt_pk_f32_fp8_sdwa v[44:45], v237 src0_sel:WORD_1
	v_cvt_pk_f32_fp8_e32 v[46:47], v241
	v_cvt_pk_f32_fp8_sdwa v[48:49], v241 src0_sel:WORD_1
	v_pk_fma_f32 v[50:51], v[42:43], v[14:15], v[50:51]
	v_pk_fma_f32 v[52:53], v[46:47], v[14:15], v[52:53]
	v_pk_fma_f32 v[50:51], v[44:45], v[16:17], v[50:51]
	v_pk_fma_f32 v[52:53], v[48:49], v[16:17], v[52:53]
	v_cvt_pk_f32_fp8_e32 v[42:43], v238
	v_cvt_pk_f32_fp8_sdwa v[44:45], v238 src0_sel:WORD_1
	v_cvt_pk_f32_fp8_e32 v[46:47], v242
	v_cvt_pk_f32_fp8_sdwa v[48:49], v242 src0_sel:WORD_1
	v_pk_fma_f32 v[50:51], v[42:43], v[18:19], v[50:51]
	v_pk_fma_f32 v[52:53], v[46:47], v[18:19], v[52:53]
	v_pk_fma_f32 v[50:51], v[44:45], v[20:21], v[50:51]
	v_pk_fma_f32 v[52:53], v[48:49], v[20:21], v[52:53]
	v_cvt_pk_f32_fp8_e32 v[42:43], v239
	v_cvt_pk_f32_fp8_sdwa v[44:45], v239 src0_sel:WORD_1
	v_cvt_pk_f32_fp8_e32 v[46:47], v243
	v_cvt_pk_f32_fp8_sdwa v[48:49], v243 src0_sel:WORD_1
	v_pk_fma_f32 v[50:51], v[42:43], v[22:23], v[50:51]
	v_pk_fma_f32 v[52:53], v[46:47], v[22:23], v[52:53]
	v_pk_fma_f32 v[50:51], v[44:45], v[24:25], v[50:51]
	v_pk_fma_f32 v[52:53], v[48:49], v[24:25], v[52:53]
	v_add_f32_e32 v38, v50, v51
	v_add_f32_e32 v39, v52, v53
	v_cvt_pk_f32_fp8_e32 v[42:43], v244
	v_cvt_pk_f32_fp8_sdwa v[44:45], v244 src0_sel:WORD_1
	v_cvt_pk_f32_fp8_e32 v[46:47], v248
	v_cvt_pk_f32_fp8_sdwa v[48:49], v248 src0_sel:WORD_1
	v_pk_mul_f32 v[50:51], v[42:43], v[10:11]
	v_pk_mul_f32 v[52:53], v[46:47], v[10:11]
	v_pk_fma_f32 v[50:51], v[44:45], v[12:13], v[50:51]
	v_pk_fma_f32 v[52:53], v[48:49], v[12:13], v[52:53]
	v_cvt_pk_f32_fp8_e32 v[42:43], v245
	v_cvt_pk_f32_fp8_sdwa v[44:45], v245 src0_sel:WORD_1
	v_cvt_pk_f32_fp8_e32 v[46:47], v249
	v_cvt_pk_f32_fp8_sdwa v[48:49], v249 src0_sel:WORD_1
	v_pk_fma_f32 v[50:51], v[42:43], v[14:15], v[50:51]
	v_pk_fma_f32 v[52:53], v[46:47], v[14:15], v[52:53]
	v_pk_fma_f32 v[50:51], v[44:45], v[16:17], v[50:51]
	v_pk_fma_f32 v[52:53], v[48:49], v[16:17], v[52:53]
	v_cvt_pk_f32_fp8_e32 v[42:43], v246
	v_cvt_pk_f32_fp8_sdwa v[44:45], v246 src0_sel:WORD_1
	v_cvt_pk_f32_fp8_e32 v[46:47], v250
	v_cvt_pk_f32_fp8_sdwa v[48:49], v250 src0_sel:WORD_1
	v_pk_fma_f32 v[50:51], v[42:43], v[18:19], v[50:51]
	v_pk_fma_f32 v[52:53], v[46:47], v[18:19], v[52:53]
	v_pk_fma_f32 v[50:51], v[44:45], v[20:21], v[50:51]
	v_pk_fma_f32 v[52:53], v[48:49], v[20:21], v[52:53]
	v_cvt_pk_f32_fp8_e32 v[42:43], v247
	v_cvt_pk_f32_fp8_sdwa v[44:45], v247 src0_sel:WORD_1
	v_cvt_pk_f32_fp8_e32 v[46:47], v251
	v_cvt_pk_f32_fp8_sdwa v[48:49], v251 src0_sel:WORD_1
	v_pk_fma_f32 v[50:51], v[42:43], v[22:23], v[50:51]
	v_pk_fma_f32 v[52:53], v[46:47], v[22:23], v[52:53]
	v_pk_fma_f32 v[50:51], v[44:45], v[24:25], v[50:51]
	v_pk_fma_f32 v[52:53], v[48:49], v[24:25], v[52:53]
	v_add_f32_e32 v40, v50, v51
	v_add_f32_e32 v41, v52, v53
	s_lshl_b32 s11, s12, 12
	v_add_u32_e32 v6, s11, v3
	v_add_f32_dpp v42, v26, v26 row_half_mirror row_mask:0xf bank_mask:0xf
	v_add_f32_dpp v43, v34, v34 row_half_mirror row_mask:0xf bank_mask:0xf
	v_cndmask_b32_e64 v26, v42, v43, s[14:15]
	v_add_f32_dpp v44, v27, v27 row_half_mirror row_mask:0xf bank_mask:0xf
	v_add_f32_dpp v45, v35, v35 row_half_mirror row_mask:0xf bank_mask:0xf
	v_cndmask_b32_e64 v27, v44, v45, s[14:15]
	v_add_f32_dpp v42, v28, v28 row_half_mirror row_mask:0xf bank_mask:0xf
	v_add_f32_dpp v43, v36, v36 row_half_mirror row_mask:0xf bank_mask:0xf
	v_cndmask_b32_e64 v28, v42, v43, s[14:15]
	v_add_f32_dpp v44, v29, v29 row_half_mirror row_mask:0xf bank_mask:0xf
	v_add_f32_dpp v45, v37, v37 row_half_mirror row_mask:0xf bank_mask:0xf
	v_cndmask_b32_e64 v29, v44, v45, s[14:15]
	v_add_f32_dpp v42, v30, v30 row_half_mirror row_mask:0xf bank_mask:0xf
	v_add_f32_dpp v43, v38, v38 row_half_mirror row_mask:0xf bank_mask:0xf
	v_cndmask_b32_e64 v30, v42, v43, s[14:15]
	v_add_f32_dpp v44, v31, v31 row_half_mirror row_mask:0xf bank_mask:0xf
	v_add_f32_dpp v45, v39, v39 row_half_mirror row_mask:0xf bank_mask:0xf
	v_cndmask_b32_e64 v31, v44, v45, s[14:15]
	v_add_f32_dpp v42, v32, v32 row_half_mirror row_mask:0xf bank_mask:0xf
	v_add_f32_dpp v43, v40, v40 row_half_mirror row_mask:0xf bank_mask:0xf
	v_cndmask_b32_e64 v32, v42, v43, s[14:15]
	v_add_f32_dpp v44, v33, v33 row_half_mirror row_mask:0xf bank_mask:0xf
	v_add_f32_dpp v45, v41, v41 row_half_mirror row_mask:0xf bank_mask:0xf
	v_cndmask_b32_e64 v33, v44, v45, s[14:15]
	s_nop 1
	v_add_f32_dpp v42, v26, v26 quad_perm:[2,3,0,1] row_mask:0xf bank_mask:0xf
	v_add_f32_dpp v43, v30, v30 quad_perm:[2,3,0,1] row_mask:0xf bank_mask:0xf
	v_cndmask_b32_e64 v26, v42, v43, s[40:41]
	v_add_f32_dpp v44, v27, v27 quad_perm:[2,3,0,1] row_mask:0xf bank_mask:0xf
	v_add_f32_dpp v45, v31, v31 quad_perm:[2,3,0,1] row_mask:0xf bank_mask:0xf
	v_cndmask_b32_e64 v27, v44, v45, s[40:41]
	v_add_f32_dpp v42, v28, v28 quad_perm:[2,3,0,1] row_mask:0xf bank_mask:0xf
	v_add_f32_dpp v43, v32, v32 quad_perm:[2,3,0,1] row_mask:0xf bank_mask:0xf
	v_cndmask_b32_e64 v28, v42, v43, s[40:41]
	v_add_f32_dpp v44, v29, v29 quad_perm:[2,3,0,1] row_mask:0xf bank_mask:0xf
	v_add_f32_dpp v45, v33, v33 quad_perm:[2,3,0,1] row_mask:0xf bank_mask:0xf
	v_cndmask_b32_e64 v29, v44, v45, s[40:41]
	s_nop 1
	v_add_f32_dpp v42, v26, v26 quad_perm:[1,0,3,2] row_mask:0xf bank_mask:0xf
	v_add_f32_dpp v43, v28, v28 quad_perm:[1,0,3,2] row_mask:0xf bank_mask:0xf
	v_cndmask_b32_e64 v26, v42, v43, s[42:43]
	v_add_f32_dpp v44, v27, v27 quad_perm:[1,0,3,2] row_mask:0xf bank_mask:0xf
	v_add_f32_dpp v45, v29, v29 quad_perm:[1,0,3,2] row_mask:0xf bank_mask:0xf
	v_cndmask_b32_e64 v27, v44, v45, s[42:43]
	s_nop 1
	v_mul_f32_e32 v26, v26, v56
	v_mul_f32_e32 v27, v27, v56
	global_store_dwordx2 v6, v[26:27], s[6:7]

; __device__ __forceinline__ float gelu_tanh(float x) {
;   float u = 0.7978845608028654f * (x + 0.044715f * x * x * x);
;   return 0.5f * x * (1.f + tanhf(u));
; }
.Lp5w_start:
	v_mbcnt_lo_u32_b32 v0, -1, 0
	v_mbcnt_hi_u32_b32 v0, -1, v0
	v_accvgpr_read_b32 v4, a129
	v_lshlrev_b32_e32 v1, 3, v0
	v_readfirstlane_b32 s8, v4
	s_lshl_b32 s10, s96, 2
	s_add_u32 s8, s8, s10
	s_lshl_b32 s9, s82, 2
	s_add_u32 s4, s80, 0x3bb5000
	s_addc_u32 s5, s81, 0
	s_add_u32 s6, s80, 0xcf35000
	s_addc_u32 s7, s81, 0
	s_mov_b32 s33, 0x3fb8aa3b
	s_mov_b32 s34, 0xc2ce8ed0
	s_mov_b32 s35, 0x42b17218
	s_mov_b32 s36, 0x3f200000
	s_brev_b32 s37, -2
	v_mov_b32_e32 v2, 0x7f800000
	v_mov_b32_e32 v3, 0x3ca908c9
	s_cmp_lt_u32 s8, 0x4200
	s_cbranch_scc0 .Lp5w_done
	s_lshl_b32 s11, s8, 12
	v_add_u32_e32 v5, s11, v1
	global_load_dwordx2 v[64:65], v5, s[6:7] offset:0
	global_load_dwordx2 v[66:67], v5, s[6:7] offset:512
	global_load_dwordx2 v[68:69], v5, s[6:7] offset:1024
	global_load_dwordx2 v[70:71], v5, s[6:7] offset:1536
	global_load_dwordx2 v[72:73], v5, s[6:7] offset:2048
	global_load_dwordx2 v[74:75], v5, s[6:7] offset:2560
	global_load_dwordx2 v[76:77], v5, s[6:7] offset:3072
	global_load_dwordx2 v[78:79], v5, s[6:7] offset:3584
	s_lshl_b32 s11, s8, 10
	v_add_u32_e32 v6, s11, v1
	global_load_dwordx2 v[80:81], v6, s[4:5] offset:512
.Lp5w_loop:
	s_add_u32 s12, s8, s9
	s_cmp_lt_u32 s12, 0x4200
	s_cbranch_scc0 .Lp5w_last0
	s_lshl_b32 s11, s12, 12
	v_add_u32_e32 v5, s11, v1
	global_load_dwordx2 v[88:89], v5, s[6:7] offset:0
	global_load_dwordx2 v[90:91], v5, s[6:7] offset:512
	global_load_dwordx2 v[92:93], v5, s[6:7] offset:1024
	global_load_dwordx2 v[94:95], v5, s[6:7] offset:1536
	global_load_dwordx2 v[96:97], v5, s[6:7] offset:2048
	global_load_dwordx2 v[98:99], v5, s[6:7] offset:2560
	global_load_dwordx2 v[100:101], v5, s[6:7] offset:3072
	global_load_dwordx2 v[102:103], v5, s[6:7] offset:3584
	s_lshl_b32 s11, s12, 10
	v_add_u32_e32 v6, s11, v1
	global_load_dwordx2 v[104:105], v6, s[4:5] offset:512
	s_waitcnt vmcnt(9)
	v_pk_add_f32 v[64:65], v[64:65], v[66:67]
	v_pk_add_f32 v[64:65], v[64:65], v[68:69]
	v_pk_add_f32 v[64:65], v[64:65], v[70:71]
	v_pk_add_f32 v[64:65], v[64:65], v[72:73]
	v_pk_add_f32 v[64:65], v[64:65], v[74:75]
	v_pk_add_f32 v[64:65], v[64:65], v[76:77]
	v_pk_add_f32 v[64:65], v[64:65], v[78:79]
	v_mul_f32_e32 v64, 0x3c800000, v64
	v_mul_f32_e32 v10, 0x3d372713, v64
	v_mul_f32_e32 v10, v64, v10
	v_fma_f32 v10, v64, v10, v64
	v_mul_f32_e32 v11, 0x3f4c422a, v10
	v_add_f32_e64 v12, |v11|, |v11|
	v_mul_f32_e32 v13, 0x3fb8aa3b, v12
	v_rndne_f32_e32 v14, v13
	v_sub_f32_e32 v15, v13, v14
	v_fma_f32 v13, v12, s33, -v13
	v_fmac_f32_e32 v13, 0x32a5705f, v12
	v_add_f32_e32 v13, v15, v13
	v_cvt_i32_f32_e32 v14, v14
	v_exp_f32_e32 v13, v13
	v_cmp_ngt_f32_e32 vcc, s34, v12
	v_ldexp_f32 v13, v13, v14
	s_nop 0
	v_cndmask_b32_e32 v13, 0, v13, vcc
	v_cmp_nlt_f32_e32 vcc, s35, v12
	s_nop 1
	v_cndmask_b32_e32 v12, v2, v13, vcc
	v_add_f32_e32 v12, 1.0, v12
	v_rcp_f32_e32 v12, v12
	s_nop 0
	v_fma_f32 v16, v12, -2.0, 1.0
	v_mul_f32_e32 v12, v11, v11
	v_fmamk_f32 v13, v12, 0xbbbac73d, v3
	v_fmaak_f32 v13, v12, v13, 0xbd5c1c4e
	v_fmaak_f32 v13, v12, v13, 0x3e088382
	v_fmaak_f32 v13, v12, v13, 0xbeaaaa99
	v_mul_f32_e64 v13, |v11|, v13
	v_fma_f32 v17, v12, v13, |v11|
	v_cmp_nlt_f32_e64 vcc, |v11|, s36
	s_nop 1
	v_cndmask_b32_e32 v16, v17, v16, vcc
	v_bfi_b32 v16, s37, v16, v11
	v_mul_f32_e32 v10, 0.5, v64
	v_add_f32_e32 v16, 1.0, v16
	v_mul_f32_e32 v10, v10, v16
	v_mul_f32_e32 v10, v80, v10
	v_mul_f32_e32 v20, 0x3d800000, v10
	v_mul_f32_e32 v65, 0x3c800000, v65
	v_mul_f32_e32 v10, 0x3d372713, v65
	v_mul_f32_e32 v10, v65, v10
	v_fma_f32 v10, v65, v10, v65
	v_mul_f32_e32 v11, 0x3f4c422a, v10
	v_add_f32_e64 v12, |v11|, |v11|
	v_mul_f32_e32 v13, 0x3fb8aa3b, v12
	v_rndne_f32_e32 v14, v13
	v_sub_f32_e32 v15, v13, v14
	v_fma_f32 v13, v12, s33, -v13
	v_fmac_f32_e32 v13, 0x32a5705f, v12
	v_add_f32_e32 v13, v15, v13
	v_cvt_i32_f32_e32 v14, v14
	v_exp_f32_e32 v13, v13
	v_cmp_ngt_f32_e32 vcc, s34, v12
	v_ldexp_f32 v13, v13, v14
	s_nop 0
	v_cndmask_b32_e32 v13, 0, v13, vcc
	v_cmp_nlt_f32_e32 vcc, s35, v12
	s_nop 1
	v_cndmask_b32_e32 v12, v2, v13, vcc
	v_add_f32_e32 v12, 1.0, v12
	v_rcp_f32_e32 v12, v12
	s_nop 0
	v_fma_f32 v16, v12, -2.0, 1.0
	v_mul_f32_e32 v12, v11, v11
	v_fmamk_f32 v13, v12, 0xbbbac73d, v3
	v_fmaak_f32 v13, v12, v13, 0xbd5c1c4e
	v_fmaak_f32 v13, v12, v13, 0x3e088382
	v_fmaak_f32 v13, v12, v13, 0xbeaaaa99
	v_mul_f32_e64 v13, |v11|, v13
	v_fma_f32 v17, v12, v13, |v11|
	v_cmp_nlt_f32_e64 vcc, |v11|, s36
	s_nop 1
	v_cndmask_b32_e32 v16, v17, v16, vcc
	v_bfi_b32 v16, s37, v16, v11
	v_mul_f32_e32 v10, 0.5, v65
	v_add_f32_e32 v16, 1.0, v16
	v_mul_f32_e32 v10, v10, v16
	v_mul_f32_e32 v10, v81, v10
	v_mul_f32_e32 v21, 0x3d800000, v10
	s_lshl_b32 s11, s8, 10
	v_add_u32_e32 v6, s11, v1
	global_store_dwordx2 v6, v[20:21], s[4:5] offset:512
	s_add_u32 s8, s12, s9
	s_cmp_lt_u32 s8, 0x4200
	s_cbranch_scc0 .Lp5w_last1
; __device__ __forceinline__ float gelu_tanh(float x) {
;   float u = 0.7978845608028654f * (x + 0.044715f * x * x * x);
;   return 0.5f * x * (1.f + tanhf(u));
; }
	s_lshl_b32 s11, s8, 12
	v_add_u32_e32 v5, s11, v1
	global_load_dwordx2 v[64:65], v5, s[6:7] offset:0
	global_load_dwordx2 v[66:67], v5, s[6:7] offset:512
	global_load_dwordx2 v[68:69], v5, s[6:7] offset:1024
	global_load_dwordx2 v[70:71], v5, s[6:7] offset:1536
	global_load_dwordx2 v[72:73], v5, s[6:7] offset:2048
	global_load_dwordx2 v[74:75], v5, s[6:7] offset:2560
	global_load_dwordx2 v[76:77], v5, s[6:7] offset:3072
	global_load_dwordx2 v[78:79], v5, s[6:7] offset:3584
	s_lshl_b32 s11, s8, 10
	v_add_u32_e32 v6, s11, v1
	global_load_dwordx2 v[80:81], v6, s[4:5] offset:512
	s_waitcnt vmcnt(9)
	v_pk_add_f32 v[88:89], v[88:89], v[90:91]
	v_pk_add_f32 v[88:89], v[88:89], v[92:93]
	v_pk_add_f32 v[88:89], v[88:89], v[94:95]
	v_pk_add_f32 v[88:89], v[88:89], v[96:97]
	v_pk_add_f32 v[88:89], v[88:89], v[98:99]
	v_pk_add_f32 v[88:89], v[88:89], v[100:101]
	v_pk_add_f32 v[88:89], v[88:89], v[102:103]
	v_mul_f32_e32 v88, 0x3c800000, v88
	v_mul_f32_e32 v10, 0x3d372713, v88
	v_mul_f32_e32 v10, v88, v10
	v_fma_f32 v10, v88, v10, v88
	v_mul_f32_e32 v11, 0x3f4c422a, v10
	v_add_f32_e64 v12, |v11|, |v11|
	v_mul_f32_e32 v13, 0x3fb8aa3b, v12
	v_rndne_f32_e32 v14, v13
	v_sub_f32_e32 v15, v13, v14
	v_fma_f32 v13, v12, s33, -v13
	v_fmac_f32_e32 v13, 0x32a5705f, v12
	v_add_f32_e32 v13, v15, v13
	v_cvt_i32_f32_e32 v14, v14
	v_exp_f32_e32 v13, v13
	v_cmp_ngt_f32_e32 vcc, s34, v12
	v_ldexp_f32 v13, v13, v14
	s_nop 0
	v_cndmask_b32_e32 v13, 0, v13, vcc
	v_cmp_nlt_f32_e32 vcc, s35, v12
	s_nop 1
	v_cndmask_b32_e32 v12, v2, v13, vcc
	v_add_f32_e32 v12, 1.0, v12
	v_rcp_f32_e32 v12, v12
	s_nop 0
	v_fma_f32 v16, v12, -2.0, 1.0
	v_mul_f32_e32 v12, v11, v11
	v_fmamk_f32 v13, v12, 0xbbbac73d, v3
	v_fmaak_f32 v13, v12, v13, 0xbd5c1c4e
	v_fmaak_f32 v13, v12, v13, 0x3e088382
	v_fmaak_f32 v13, v12, v13, 0xbeaaaa99
	v_mul_f32_e64 v13, |v11|, v13
	v_fma_f32 v17, v12, v13, |v11|
	v_cmp_nlt_f32_e64 vcc, |v11|, s36
	s_nop 1
	v_cndmask_b32_e32 v16, v17, v16, vcc
	v_bfi_b32 v16, s37, v16, v11
	v_mul_f32_e32 v10, 0.5, v88
	v_add_f32_e32 v16, 1.0, v16
	v_mul_f32_e32 v10, v10, v16
	v_mul_f32_e32 v10, v104, v10
	v_mul_f32_e32 v20, 0x3d800000, v10
	v_mul_f32_e32 v89, 0x3c800000, v89
	v_mul_f32_e32 v10, 0x3d372713, v89
	v_mul_f32_e32 v10, v89, v10
	v_fma_f32 v10, v89, v10, v89
	v_mul_f32_e32 v11, 0x3f4c422a, v10
	v_add_f32_e64 v12, |v11|, |v11|
	v_mul_f32_e32 v13, 0x3fb8aa3b, v12
	v_rndne_f32_e32 v14, v13
	v_sub_f32_e32 v15, v13, v14
	v_fma_f32 v13, v12, s33, -v13
	v_fmac_f32_e32 v13, 0x32a5705f, v12
	v_add_f32_e32 v13, v15, v13
	v_cvt_i32_f32_e32 v14, v14
	v_exp_f32_e32 v13, v13
	v_cmp_ngt_f32_e32 vcc, s34, v12
	v_ldexp_f32 v13, v13, v14
	s_nop 0
	v_cndmask_b32_e32 v13, 0, v13, vcc
	v_cmp_nlt_f32_e32 vcc, s35, v12
	s_nop 1
	v_cndmask_b32_e32 v12, v2, v13, vcc
	v_add_f32_e32 v12, 1.0, v12
	v_rcp_f32_e32 v12, v12
	s_nop 0
	v_fma_f32 v16, v12, -2.0, 1.0
	v_mul_f32_e32 v12, v11, v11
	v_fmamk_f32 v13, v12, 0xbbbac73d, v3
	v_fmaak_f32 v13, v12, v13, 0xbd5c1c4e
	v_fmaak_f32 v13, v12, v13, 0x3e088382
	v_fmaak_f32 v13, v12, v13, 0xbeaaaa99
	v_mul_f32_e64 v13, |v11|, v13
	v_fma_f32 v17, v12, v13, |v11|
	v_cmp_nlt_f32_e64 vcc, |v11|, s36
	s_nop 1
	v_cndmask_b32_e32 v16, v17, v16, vcc
	v_bfi_b32 v16, s37, v16, v11
	v_mul_f32_e32 v10, 0.5, v89
	v_add_f32_e32 v16, 1.0, v16
	v_mul_f32_e32 v10, v10, v16
	v_mul_f32_e32 v10, v105, v10
	v_mul_f32_e32 v21, 0x3d800000, v10
	s_lshl_b32 s11, s12, 10
	v_add_u32_e32 v6, s11, v1
	global_store_dwordx2 v6, v[20:21], s[4:5] offset:512
	s_branch .Lp5w_loop
; __device__ __forceinline__ float gelu_tanh(float x) {
;   float u = 0.7978845608028654f * (x + 0.044715f * x * x * x);
;   return 0.5f * x * (1.f + tanhf(u));
; }
.Lp5w_last0:
	s_waitcnt vmcnt(0)
	v_pk_add_f32 v[64:65], v[64:65], v[66:67]
	v_pk_add_f32 v[64:65], v[64:65], v[68:69]
	v_pk_add_f32 v[64:65], v[64:65], v[70:71]
	v_pk_add_f32 v[64:65], v[64:65], v[72:73]
	v_pk_add_f32 v[64:65], v[64:65], v[74:75]
	v_pk_add_f32 v[64:65], v[64:65], v[76:77]
	v_pk_add_f32 v[64:65], v[64:65], v[78:79]
	v_mul_f32_e32 v64, 0x3c800000, v64
	v_mul_f32_e32 v10, 0x3d372713, v64
	v_mul_f32_e32 v10, v64, v10
	v_fma_f32 v10, v64, v10, v64
	v_mul_f32_e32 v11, 0x3f4c422a, v10
	v_add_f32_e64 v12, |v11|, |v11|
	v_mul_f32_e32 v13, 0x3fb8aa3b, v12
	v_rndne_f32_e32 v14, v13
	v_sub_f32_e32 v15, v13, v14
	v_fma_f32 v13, v12, s33, -v13
	v_fmac_f32_e32 v13, 0x32a5705f, v12
	v_add_f32_e32 v13, v15, v13
	v_cvt_i32_f32_e32 v14, v14
	v_exp_f32_e32 v13, v13
	v_cmp_ngt_f32_e32 vcc, s34, v12
	v_ldexp_f32 v13, v13, v14
	s_nop 0
	v_cndmask_b32_e32 v13, 0, v13, vcc
	v_cmp_nlt_f32_e32 vcc, s35, v12
	s_nop 1
	v_cndmask_b32_e32 v12, v2, v13, vcc
	v_add_f32_e32 v12, 1.0, v12
	v_rcp_f32_e32 v12, v12
	s_nop 0
	v_fma_f32 v16, v12, -2.0, 1.0
	v_mul_f32_e32 v12, v11, v11
	v_fmamk_f32 v13, v12, 0xbbbac73d, v3
	v_fmaak_f32 v13, v12, v13, 0xbd5c1c4e
	v_fmaak_f32 v13, v12, v13, 0x3e088382
	v_fmaak_f32 v13, v12, v13, 0xbeaaaa99
	v_mul_f32_e64 v13, |v11|, v13
	v_fma_f32 v17, v12, v13, |v11|
	v_cmp_nlt_f32_e64 vcc, |v11|, s36
	s_nop 1
	v_cndmask_b32_e32 v16, v17, v16, vcc
	v_bfi_b32 v16, s37, v16, v11
	v_mul_f32_e32 v10, 0.5, v64
	v_add_f32_e32 v16, 1.0, v16
	v_mul_f32_e32 v10, v10, v16
	v_mul_f32_e32 v10, v80, v10
	v_mul_f32_e32 v20, 0x3d800000, v10
	v_mul_f32_e32 v65, 0x3c800000, v65
	v_mul_f32_e32 v10, 0x3d372713, v65
	v_mul_f32_e32 v10, v65, v10
	v_fma_f32 v10, v65, v10, v65
	v_mul_f32_e32 v11, 0x3f4c422a, v10
	v_add_f32_e64 v12, |v11|, |v11|
	v_mul_f32_e32 v13, 0x3fb8aa3b, v12
	v_rndne_f32_e32 v14, v13
	v_sub_f32_e32 v15, v13, v14
	v_fma_f32 v13, v12, s33, -v13
	v_fmac_f32_e32 v13, 0x32a5705f, v12
	v_add_f32_e32 v13, v15, v13
	v_cvt_i32_f32_e32 v14, v14
	v_exp_f32_e32 v13, v13
	v_cmp_ngt_f32_e32 vcc, s34, v12
	v_ldexp_f32 v13, v13, v14
	s_nop 0
	v_cndmask_b32_e32 v13, 0, v13, vcc
	v_cmp_nlt_f32_e32 vcc, s35, v12
	s_nop 1
	v_cndmask_b32_e32 v12, v2, v13, vcc
	v_add_f32_e32 v12, 1.0, v12
	v_rcp_f32_e32 v12, v12
	s_nop 0
	v_fma_f32 v16, v12, -2.0, 1.0
	v_mul_f32_e32 v12, v11, v11
	v_fmamk_f32 v13, v12, 0xbbbac73d, v3
	v_fmaak_f32 v13, v12, v13, 0xbd5c1c4e
	v_fmaak_f32 v13, v12, v13, 0x3e088382
	v_fmaak_f32 v13, v12, v13, 0xbeaaaa99
	v_mul_f32_e64 v13, |v11|, v13
	v_fma_f32 v17, v12, v13, |v11|
	v_cmp_nlt_f32_e64 vcc, |v11|, s36
	s_nop 1
	v_cndmask_b32_e32 v16, v17, v16, vcc
	v_bfi_b32 v16, s37, v16, v11
	v_mul_f32_e32 v10, 0.5, v65
	v_add_f32_e32 v16, 1.0, v16
	v_mul_f32_e32 v10, v10, v16
	v_mul_f32_e32 v10, v81, v10
	v_mul_f32_e32 v21, 0x3d800000, v10
	s_lshl_b32 s11, s8, 10
	v_add_u32_e32 v6, s11, v1
	global_store_dwordx2 v6, v[20:21], s[4:5] offset:512
	s_branch .Lp5w_done
.Lp5w_last1:
	s_waitcnt vmcnt(0)
	v_pk_add_f32 v[88:89], v[88:89], v[90:91]
	v_pk_add_f32 v[88:89], v[88:89], v[92:93]
	v_pk_add_f32 v[88:89], v[88:89], v[94:95]
	v_pk_add_f32 v[88:89], v[88:89], v[96:97]
	v_pk_add_f32 v[88:89], v[88:89], v[98:99]
	v_pk_add_f32 v[88:89], v[88:89], v[100:101]
	v_pk_add_f32 v[88:89], v[88:89], v[102:103]
	v_mul_f32_e32 v88, 0x3c800000, v88
	v_mul_f32_e32 v10, 0x3d372713, v88
	v_mul_f32_e32 v10, v88, v10
	v_fma_f32 v10, v88, v10, v88
	v_mul_f32_e32 v11, 0x3f4c422a, v10
	v_add_f32_e64 v12, |v11|, |v11|
	v_mul_f32_e32 v13, 0x3fb8aa3b, v12
	v_rndne_f32_e32 v14, v13
	v_sub_f32_e32 v15, v13, v14
	v_fma_f32 v13, v12, s33, -v13
	v_fmac_f32_e32 v13, 0x32a5705f, v12
	v_add_f32_e32 v13, v15, v13
	v_cvt_i32_f32_e32 v14, v14
	v_exp_f32_e32 v13, v13
	v_cmp_ngt_f32_e32 vcc, s34, v12
	v_ldexp_f32 v13, v13, v14
	s_nop 0
	v_cndmask_b32_e32 v13, 0, v13, vcc
	v_cmp_nlt_f32_e32 vcc, s35, v12
	s_nop 1
	v_cndmask_b32_e32 v12, v2, v13, vcc
	v_add_f32_e32 v12, 1.0, v12
	v_rcp_f32_e32 v12, v12
	s_nop 0
	v_fma_f32 v16, v12, -2.0, 1.0
	v_mul_f32_e32 v12, v11, v11
	v_fmamk_f32 v13, v12, 0xbbbac73d, v3
	v_fmaak_f32 v13, v12, v13, 0xbd5c1c4e
	v_fmaak_f32 v13, v12, v13, 0x3e088382
	v_fmaak_f32 v13, v12, v13, 0xbeaaaa99
	v_mul_f32_e64 v13, |v11|, v13
	v_fma_f32 v17, v12, v13, |v11|
	v_cmp_nlt_f32_e64 vcc, |v11|, s36
	s_nop 1
	v_cndmask_b32_e32 v16, v17, v16, vcc
	v_bfi_b32 v16, s37, v16, v11
	v_mul_f32_e32 v10, 0.5, v88
	v_add_f32_e32 v16, 1.0, v16
	v_mul_f32_e32 v10, v10, v16
	v_mul_f32_e32 v10, v104, v10
	v_mul_f32_e32 v20, 0x3d800000, v10
	v_mul_f32_e32 v89, 0x3c800000, v89
	v_mul_f32_e32 v10, 0x3d372713, v89
	v_mul_f32_e32 v10, v89, v10
	v_fma_f32 v10, v89, v10, v89
	v_mul_f32_e32 v11, 0x3f4c422a, v10
	v_add_f32_e64 v12, |v11|, |v11|
	v_mul_f32_e32 v13, 0x3fb8aa3b, v12
	v_rndne_f32_e32 v14, v13
	v_sub_f32_e32 v15, v13, v14
	v_fma_f32 v13, v12, s33, -v13
	v_fmac_f32_e32 v13, 0x32a5705f, v12
	v_add_f32_e32 v13, v15, v13
	v_cvt_i32_f32_e32 v14, v14
	v_exp_f32_e32 v13, v13
	v_cmp_ngt_f32_e32 vcc, s34, v12
	v_ldexp_f32 v13, v13, v14
	s_nop 0
	v_cndmask_b32_e32 v13, 0, v13, vcc
	v_cmp_nlt_f32_e32 vcc, s35, v12
	s_nop 1
	v_cndmask_b32_e32 v12, v2, v13, vcc
	v_add_f32_e32 v12, 1.0, v12
	v_rcp_f32_e32 v12, v12
	s_nop 0
	v_fma_f32 v16, v12, -2.0, 1.0
	v_mul_f32_e32 v12, v11, v11
	v_fmamk_f32 v13, v12, 0xbbbac73d, v3
	v_fmaak_f32 v13, v12, v13, 0xbd5c1c4e
	v_fmaak_f32 v13, v12, v13, 0x3e088382
	v_fmaak_f32 v13, v12, v13, 0xbeaaaa99
	v_mul_f32_e64 v13, |v11|, v13
	v_fma_f32 v17, v12, v13, |v11|
	v_cmp_nlt_f32_e64 vcc, |v11|, s36
	s_nop 1
	v_cndmask_b32_e32 v16, v17, v16, vcc
	v_bfi_b32 v16, s37, v16, v11
	v_mul_f32_e32 v10, 0.5, v89
	v_add_f32_e32 v16, 1.0, v16
	v_mul_f32_e32 v10, v10, v16
	v_mul_f32_e32 v10, v105, v10
	v_mul_f32_e32 v21, 0x3d800000, v10
	s_lshl_b32 s11, s12, 10
	v_add_u32_e32 v6, s11, v1
	global_store_dwordx2 v6, v[20:21], s[4:5] offset:512
